# stepper waves raised to prio 3; residual GEMM epilogues (W2, WO l>0) turned from a serialized load-wait-store ladder into a 10-deep rolling pipeline with counted vmcnt
# speedup vs baseline: 1.0323x; 1.0033x over previous
.LBB0_97:
	v_lshl_add_u32 v176, s46, 8, v178
	v_lshl_or_b32 v76, s84, 8, v180
	s_lshl_b64 s[16:17], s[16:17], 2
	v_ashrrev_i32_e32 v177, 31, v176
	s_add_u32 s16, s72, s16
	v_ashrrev_i32_e32 v77, 31, v76
	v_lshlrev_b64 v[172:173], 12, v[176:177]
	s_addc_u32 s17, s73, s17
	v_lshlrev_b64 v[174:175], 2, v[76:77]
	v_lshl_add_u64 v[172:173], s[0:1], 0, v[172:173]
	v_lshl_add_u64 v[76:77], s[16:17], 0, v[174:175]
	v_lshl_add_u64 v[172:173], v[172:173], 0, v[174:175]
	global_load_dwordx4 v[96:99], v[76:77], off
	global_load_dwordx4 v[88:91], v[76:77], off offset:64
	global_load_dwordx4 v[84:87], v[76:77], off offset:128
	s_nop 0
	global_load_dwordx4 v[76:79], v[76:77], off offset:192
	s_mov_b64 s[16:17], 0x80000
	s_mov_b64 s[16:17], 0x10000
	v_lshl_add_u64 v[186:187], v[172:173], 0, s[16:17]
	s_mov_b64 s[16:17], 0x20000
	v_lshl_add_u64 v[222:223], v[172:173], 0, s[16:17]
	s_mov_b64 s[16:17], 0x30000
	v_lshl_add_u64 v[224:225], v[172:173], 0, s[16:17]
	s_mov_b64 s[16:17], 0x80000
	v_lshl_add_u64 v[226:227], v[172:173], 0, s[16:17]
	s_mov_b64 s[16:17], 0x90000
	v_lshl_add_u64 v[228:229], v[172:173], 0, s[16:17]
	s_mov_b64 s[16:17], 0xa0000
	v_lshl_add_u64 v[230:231], v[172:173], 0, s[16:17]
	s_mov_b64 s[16:17], 0xb0000
	v_lshl_add_u64 v[232:233], v[172:173], 0, s[16:17]
	global_load_dwordx4 v[174:177], v[172:173], off
	global_load_dwordx4 v[182:185], v[172:173], off offset:64
	global_load_dwordx4 v[190:193], v[172:173], off offset:128
	global_load_dwordx4 v[194:197], v[172:173], off offset:192
	global_load_dwordx4 v[198:201], v[186:187], off
	global_load_dwordx4 v[202:205], v[186:187], off offset:64
	global_load_dwordx4 v[206:209], v[186:187], off offset:128
	global_load_dwordx4 v[210:213], v[186:187], off offset:192
	global_load_dwordx4 v[214:217], v[222:223], off
	global_load_dwordx4 v[218:221], v[222:223], off offset:64
	s_waitcnt vmcnt(9)
	v_pk_fma_f32 v[142:143], v[142:143], v[98:99], v[176:177]
	v_pk_fma_f32 v[140:141], v[140:141], v[96:97], v[174:175]
	global_store_dwordx4 v[172:173], v[140:143], off
	global_load_dwordx4 v[174:177], v[222:223], off offset:128
	s_waitcnt vmcnt(10)
	v_pk_fma_f32 v[138:139], v[138:139], v[90:91], v[184:185]
	v_pk_fma_f32 v[136:137], v[136:137], v[88:89], v[182:183]
	global_store_dwordx4 v[172:173], v[136:139], off offset:64
	global_load_dwordx4 v[182:185], v[222:223], off offset:192
	s_waitcnt vmcnt(11)
	v_pk_fma_f32 v[134:135], v[134:135], v[86:87], v[192:193]
	v_pk_fma_f32 v[132:133], v[132:133], v[84:85], v[190:191]
	global_store_dwordx4 v[172:173], v[132:135], off offset:128
	global_load_dwordx4 v[190:193], v[224:225], off
	s_waitcnt vmcnt(12)
	v_pk_fma_f32 v[130:131], v[130:131], v[78:79], v[196:197]
	v_pk_fma_f32 v[128:129], v[128:129], v[76:77], v[194:195]
	global_store_dwordx4 v[172:173], v[128:131], off offset:192
	global_load_dwordx4 v[194:197], v[224:225], off offset:64
	s_waitcnt vmcnt(13)
	v_pk_fma_f32 v[126:127], v[126:127], v[98:99], v[200:201]
	v_pk_fma_f32 v[124:125], v[124:125], v[96:97], v[198:199]
	global_store_dwordx4 v[186:187], v[124:127], off
	global_load_dwordx4 v[198:201], v[224:225], off offset:128
	s_waitcnt vmcnt(14)
	v_pk_fma_f32 v[122:123], v[122:123], v[90:91], v[204:205]
	v_pk_fma_f32 v[120:121], v[120:121], v[88:89], v[202:203]
	global_store_dwordx4 v[186:187], v[120:123], off offset:64
	global_load_dwordx4 v[202:205], v[224:225], off offset:192
	s_waitcnt vmcnt(15)
	v_pk_fma_f32 v[118:119], v[118:119], v[86:87], v[208:209]
	v_pk_fma_f32 v[116:117], v[116:117], v[84:85], v[206:207]
	global_store_dwordx4 v[186:187], v[116:119], off offset:128
	global_load_dwordx4 v[206:209], v[226:227], off
	s_waitcnt vmcnt(16)
	v_pk_fma_f32 v[114:115], v[114:115], v[78:79], v[212:213]
	v_pk_fma_f32 v[112:113], v[112:113], v[76:77], v[210:211]
	global_store_dwordx4 v[186:187], v[112:115], off offset:192
	global_load_dwordx4 v[210:213], v[226:227], off offset:64
	s_waitcnt vmcnt(17)
	v_pk_fma_f32 v[110:111], v[110:111], v[98:99], v[216:217]
	v_pk_fma_f32 v[108:109], v[108:109], v[96:97], v[214:215]
	global_store_dwordx4 v[222:223], v[108:111], off
	global_load_dwordx4 v[214:217], v[226:227], off offset:128
	s_waitcnt vmcnt(18)
	v_pk_fma_f32 v[106:107], v[106:107], v[90:91], v[220:221]
	v_pk_fma_f32 v[104:105], v[104:105], v[88:89], v[218:219]
	global_store_dwordx4 v[222:223], v[104:107], off offset:64
	global_load_dwordx4 v[218:221], v[226:227], off offset:192
	s_waitcnt vmcnt(18)
	v_pk_fma_f32 v[102:103], v[102:103], v[86:87], v[176:177]
	v_pk_fma_f32 v[100:101], v[100:101], v[84:85], v[174:175]
	global_store_dwordx4 v[222:223], v[100:103], off offset:128
	global_load_dwordx4 v[174:177], v[228:229], off
	s_waitcnt vmcnt(18)
	v_pk_fma_f32 v[94:95], v[94:95], v[78:79], v[184:185]
	v_pk_fma_f32 v[92:93], v[92:93], v[76:77], v[182:183]
	global_store_dwordx4 v[222:223], v[92:95], off offset:192
	global_load_dwordx4 v[182:185], v[228:229], off offset:64
	s_waitcnt vmcnt(18)
	v_pk_fma_f32 v[82:83], v[82:83], v[98:99], v[192:193]
	v_pk_fma_f32 v[80:81], v[80:81], v[96:97], v[190:191]
	global_store_dwordx4 v[224:225], v[80:83], off
	global_load_dwordx4 v[190:193], v[228:229], off offset:128
	s_waitcnt vmcnt(18)
	v_pk_fma_f32 v[74:75], v[74:75], v[90:91], v[196:197]
	v_pk_fma_f32 v[72:73], v[72:73], v[88:89], v[194:195]
	global_store_dwordx4 v[224:225], v[72:75], off offset:64
	global_load_dwordx4 v[194:197], v[228:229], off offset:192
	s_waitcnt vmcnt(18)
	v_pk_fma_f32 v[70:71], v[70:71], v[86:87], v[200:201]
	v_pk_fma_f32 v[68:69], v[68:69], v[84:85], v[198:199]
	global_store_dwordx4 v[224:225], v[68:71], off offset:128
	global_load_dwordx4 v[198:201], v[230:231], off
	s_waitcnt vmcnt(18)
	v_pk_fma_f32 v[66:67], v[66:67], v[78:79], v[204:205]
	v_pk_fma_f32 v[64:65], v[64:65], v[76:77], v[202:203]
	global_store_dwordx4 v[224:225], v[64:67], off offset:192
	global_load_dwordx4 v[202:205], v[230:231], off offset:64
	s_waitcnt vmcnt(18)
	v_pk_fma_f32 v[62:63], v[62:63], v[98:99], v[208:209]
	v_pk_fma_f32 v[60:61], v[60:61], v[96:97], v[206:207]
	global_store_dwordx4 v[226:227], v[60:63], off
	global_load_dwordx4 v[206:209], v[230:231], off offset:128
	s_waitcnt vmcnt(18)
	v_pk_fma_f32 v[58:59], v[58:59], v[90:91], v[212:213]
	v_pk_fma_f32 v[56:57], v[56:57], v[88:89], v[210:211]
	global_store_dwordx4 v[226:227], v[56:59], off offset:64
	global_load_dwordx4 v[210:213], v[230:231], off offset:192
	s_waitcnt vmcnt(18)
	v_pk_fma_f32 v[54:55], v[54:55], v[86:87], v[216:217]
	v_pk_fma_f32 v[52:53], v[52:53], v[84:85], v[214:215]
	global_store_dwordx4 v[226:227], v[52:55], off offset:128
	global_load_dwordx4 v[214:217], v[232:233], off
	s_waitcnt vmcnt(18)
	v_pk_fma_f32 v[50:51], v[50:51], v[78:79], v[220:221]
	v_pk_fma_f32 v[48:49], v[48:49], v[76:77], v[218:219]
	global_store_dwordx4 v[226:227], v[48:51], off offset:192
	global_load_dwordx4 v[218:221], v[232:233], off offset:64
	s_waitcnt vmcnt(18)
	v_pk_fma_f32 v[46:47], v[46:47], v[98:99], v[176:177]
	v_pk_fma_f32 v[44:45], v[44:45], v[96:97], v[174:175]
	global_store_dwordx4 v[228:229], v[44:47], off
	global_load_dwordx4 v[174:177], v[232:233], off offset:128
	s_waitcnt vmcnt(18)
	v_pk_fma_f32 v[42:43], v[42:43], v[90:91], v[184:185]
	v_pk_fma_f32 v[40:41], v[40:41], v[88:89], v[182:183]
	global_store_dwordx4 v[228:229], v[40:43], off offset:64
	global_load_dwordx4 v[182:185], v[232:233], off offset:192
	s_waitcnt vmcnt(18)
	v_pk_fma_f32 v[38:39], v[38:39], v[86:87], v[192:193]
	v_pk_fma_f32 v[36:37], v[36:37], v[84:85], v[190:191]
	global_store_dwordx4 v[228:229], v[36:39], off offset:128
	s_waitcnt vmcnt(17)
	v_pk_fma_f32 v[34:35], v[34:35], v[78:79], v[196:197]
	v_pk_fma_f32 v[32:33], v[32:33], v[76:77], v[194:195]
	global_store_dwordx4 v[228:229], v[32:35], off offset:192
	s_waitcnt vmcnt(16)
	v_pk_fma_f32 v[30:31], v[30:31], v[98:99], v[200:201]
	v_pk_fma_f32 v[28:29], v[28:29], v[96:97], v[198:199]
	global_store_dwordx4 v[230:231], v[28:31], off
	s_waitcnt vmcnt(15)
	v_pk_fma_f32 v[26:27], v[26:27], v[90:91], v[204:205]
	v_pk_fma_f32 v[24:25], v[24:25], v[88:89], v[202:203]
	global_store_dwordx4 v[230:231], v[24:27], off offset:64
	s_waitcnt vmcnt(14)
	v_pk_fma_f32 v[22:23], v[22:23], v[86:87], v[208:209]
	v_pk_fma_f32 v[20:21], v[20:21], v[84:85], v[206:207]
	global_store_dwordx4 v[230:231], v[20:23], off offset:128
	s_waitcnt vmcnt(13)
	v_pk_fma_f32 v[18:19], v[18:19], v[78:79], v[212:213]
	v_pk_fma_f32 v[16:17], v[16:17], v[76:77], v[210:211]
	global_store_dwordx4 v[230:231], v[16:19], off offset:192
	s_waitcnt vmcnt(12)
	v_pk_fma_f32 v[14:15], v[14:15], v[98:99], v[216:217]
	v_pk_fma_f32 v[12:13], v[12:13], v[96:97], v[214:215]
	global_store_dwordx4 v[232:233], v[12:15], off
	s_waitcnt vmcnt(11)
	v_pk_fma_f32 v[10:11], v[10:11], v[90:91], v[220:221]
	v_pk_fma_f32 v[8:9], v[8:9], v[88:89], v[218:219]
	global_store_dwordx4 v[232:233], v[8:11], off offset:64
	s_waitcnt vmcnt(10)
	v_pk_fma_f32 v[6:7], v[6:7], v[86:87], v[176:177]
	v_pk_fma_f32 v[4:5], v[4:5], v[84:85], v[174:175]
	global_store_dwordx4 v[232:233], v[4:7], off offset:128
	s_waitcnt vmcnt(9)
	v_pk_fma_f32 v[2:3], v[2:3], v[78:79], v[184:185]
	v_pk_fma_f32 v[0:1], v[0:1], v[76:77], v[182:183]
	global_store_dwordx4 v[232:233], v[0:3], off offset:192
	s_mov_b32 s11, 0xb0000
	s_mov_b64 s[16:17], -1
	s_andn2_b64 vcc, exec, s[38:39]
	s_cbranch_vccnz .LBB0_88
	s_andn2_b64 vcc, exec, s[2:3]
	s_cbranch_vccnz .LBB0_87
	s_barrier
	s_branch .LBB0_87

.LBB0_267:
	v_lshl_add_u32 v174, s88, 8, v184
	v_lshl_or_b32 v76, s89, 8, v186
	s_lshl_b64 s[0:1], s[0:1], 2
	v_ashrrev_i32_e32 v175, 31, v174
	s_add_u32 s0, s65, s0
	v_ashrrev_i32_e32 v77, 31, v76
	v_lshlrev_b64 v[170:171], 12, v[174:175]
	s_addc_u32 s1, s70, s1
	v_lshlrev_b64 v[172:173], 2, v[76:77]
	v_lshl_add_u64 v[170:171], s[2:3], 0, v[170:171]
	v_lshl_add_u64 v[76:77], s[0:1], 0, v[172:173]
	v_lshl_add_u64 v[170:171], v[170:171], 0, v[172:173]
	global_load_dwordx4 v[96:99], v[76:77], off
	global_load_dwordx4 v[88:91], v[76:77], off offset:64
	global_load_dwordx4 v[84:87], v[76:77], off offset:128
	s_nop 0
	global_load_dwordx4 v[76:79], v[76:77], off offset:192
	s_mov_b64 s[0:1], 0x80000
	s_mov_b64 s[0:1], 0x10000
	v_lshl_add_u64 v[226:227], v[170:171], 0, s[0:1]
	s_mov_b64 s[0:1], 0x20000
	v_lshl_add_u64 v[228:229], v[170:171], 0, s[0:1]
	s_mov_b64 s[0:1], 0x30000
	v_lshl_add_u64 v[230:231], v[170:171], 0, s[0:1]
	s_mov_b64 s[0:1], 0x80000
	v_lshl_add_u64 v[232:233], v[170:171], 0, s[0:1]
	s_mov_b64 s[0:1], 0x90000
	v_lshl_add_u64 v[234:235], v[170:171], 0, s[0:1]
	s_mov_b64 s[0:1], 0xa0000
	v_lshl_add_u64 v[236:237], v[170:171], 0, s[0:1]
	s_mov_b64 s[0:1], 0xb0000
	v_lshl_add_u64 v[238:239], v[170:171], 0, s[0:1]
	global_load_dwordx4 v[172:175], v[170:171], off
	global_load_dwordx4 v[190:193], v[170:171], off offset:64
	global_load_dwordx4 v[194:197], v[170:171], off offset:128
	global_load_dwordx4 v[198:201], v[170:171], off offset:192
	global_load_dwordx4 v[202:205], v[226:227], off
	global_load_dwordx4 v[206:209], v[226:227], off offset:64
	global_load_dwordx4 v[210:213], v[226:227], off offset:128
	global_load_dwordx4 v[214:217], v[226:227], off offset:192
	global_load_dwordx4 v[218:221], v[228:229], off
	global_load_dwordx4 v[222:225], v[228:229], off offset:64
	s_waitcnt vmcnt(9)
	v_pk_fma_f32 v[142:143], v[142:143], v[98:99], v[174:175]
	v_pk_fma_f32 v[140:141], v[140:141], v[96:97], v[172:173]
	global_store_dwordx4 v[170:171], v[140:143], off
	global_load_dwordx4 v[172:175], v[228:229], off offset:128
	s_waitcnt vmcnt(10)
	v_pk_fma_f32 v[138:139], v[138:139], v[90:91], v[192:193]
	v_pk_fma_f32 v[136:137], v[136:137], v[88:89], v[190:191]
	global_store_dwordx4 v[170:171], v[136:139], off offset:64
	global_load_dwordx4 v[190:193], v[228:229], off offset:192
	s_waitcnt vmcnt(11)
	v_pk_fma_f32 v[134:135], v[134:135], v[86:87], v[196:197]
	v_pk_fma_f32 v[132:133], v[132:133], v[84:85], v[194:195]
	global_store_dwordx4 v[170:171], v[132:135], off offset:128
	global_load_dwordx4 v[194:197], v[230:231], off
	s_waitcnt vmcnt(12)
	v_pk_fma_f32 v[130:131], v[130:131], v[78:79], v[200:201]
	v_pk_fma_f32 v[128:129], v[128:129], v[76:77], v[198:199]
	global_store_dwordx4 v[170:171], v[128:131], off offset:192
	global_load_dwordx4 v[198:201], v[230:231], off offset:64
	s_waitcnt vmcnt(13)
	v_pk_fma_f32 v[126:127], v[126:127], v[98:99], v[204:205]
	v_pk_fma_f32 v[124:125], v[124:125], v[96:97], v[202:203]
	global_store_dwordx4 v[226:227], v[124:127], off
	global_load_dwordx4 v[202:205], v[230:231], off offset:128
	s_waitcnt vmcnt(14)
	v_pk_fma_f32 v[122:123], v[122:123], v[90:91], v[208:209]
	v_pk_fma_f32 v[120:121], v[120:121], v[88:89], v[206:207]
	global_store_dwordx4 v[226:227], v[120:123], off offset:64
	global_load_dwordx4 v[206:209], v[230:231], off offset:192
	s_waitcnt vmcnt(15)
	v_pk_fma_f32 v[118:119], v[118:119], v[86:87], v[212:213]
	v_pk_fma_f32 v[116:117], v[116:117], v[84:85], v[210:211]
	global_store_dwordx4 v[226:227], v[116:119], off offset:128
	global_load_dwordx4 v[210:213], v[232:233], off
	s_waitcnt vmcnt(16)
	v_pk_fma_f32 v[114:115], v[114:115], v[78:79], v[216:217]
	v_pk_fma_f32 v[112:113], v[112:113], v[76:77], v[214:215]
	global_store_dwordx4 v[226:227], v[112:115], off offset:192
	global_load_dwordx4 v[214:217], v[232:233], off offset:64
	s_waitcnt vmcnt(17)
	v_pk_fma_f32 v[110:111], v[110:111], v[98:99], v[220:221]
	v_pk_fma_f32 v[108:109], v[108:109], v[96:97], v[218:219]
	global_store_dwordx4 v[228:229], v[108:111], off
	global_load_dwordx4 v[218:221], v[232:233], off offset:128
	s_waitcnt vmcnt(18)
	v_pk_fma_f32 v[106:107], v[106:107], v[90:91], v[224:225]
	v_pk_fma_f32 v[104:105], v[104:105], v[88:89], v[222:223]
	global_store_dwordx4 v[228:229], v[104:107], off offset:64
	global_load_dwordx4 v[222:225], v[232:233], off offset:192
	s_waitcnt vmcnt(18)
	v_pk_fma_f32 v[102:103], v[102:103], v[86:87], v[174:175]
	v_pk_fma_f32 v[100:101], v[100:101], v[84:85], v[172:173]
	global_store_dwordx4 v[228:229], v[100:103], off offset:128
	global_load_dwordx4 v[172:175], v[234:235], off
	s_waitcnt vmcnt(18)
	v_pk_fma_f32 v[94:95], v[94:95], v[78:79], v[192:193]
	v_pk_fma_f32 v[92:93], v[92:93], v[76:77], v[190:191]
	global_store_dwordx4 v[228:229], v[92:95], off offset:192
	global_load_dwordx4 v[190:193], v[234:235], off offset:64
	s_waitcnt vmcnt(18)
	v_pk_fma_f32 v[82:83], v[82:83], v[98:99], v[196:197]
	v_pk_fma_f32 v[80:81], v[80:81], v[96:97], v[194:195]
	global_store_dwordx4 v[230:231], v[80:83], off
	global_load_dwordx4 v[194:197], v[234:235], off offset:128
	s_waitcnt vmcnt(18)
	v_pk_fma_f32 v[74:75], v[74:75], v[90:91], v[200:201]
	v_pk_fma_f32 v[72:73], v[72:73], v[88:89], v[198:199]
	global_store_dwordx4 v[230:231], v[72:75], off offset:64
	global_load_dwordx4 v[198:201], v[234:235], off offset:192
	s_waitcnt vmcnt(18)
	v_pk_fma_f32 v[70:71], v[70:71], v[86:87], v[204:205]
	v_pk_fma_f32 v[68:69], v[68:69], v[84:85], v[202:203]
	global_store_dwordx4 v[230:231], v[68:71], off offset:128
	global_load_dwordx4 v[202:205], v[236:237], off
	s_waitcnt vmcnt(18)
	v_pk_fma_f32 v[66:67], v[66:67], v[78:79], v[208:209]
	v_pk_fma_f32 v[64:65], v[64:65], v[76:77], v[206:207]
	global_store_dwordx4 v[230:231], v[64:67], off offset:192
	global_load_dwordx4 v[206:209], v[236:237], off offset:64
	s_waitcnt vmcnt(18)
	v_pk_fma_f32 v[62:63], v[62:63], v[98:99], v[212:213]
	v_pk_fma_f32 v[60:61], v[60:61], v[96:97], v[210:211]
	global_store_dwordx4 v[232:233], v[60:63], off
	global_load_dwordx4 v[210:213], v[236:237], off offset:128
	s_waitcnt vmcnt(18)
	v_pk_fma_f32 v[58:59], v[58:59], v[90:91], v[216:217]
	v_pk_fma_f32 v[56:57], v[56:57], v[88:89], v[214:215]
	global_store_dwordx4 v[232:233], v[56:59], off offset:64
	global_load_dwordx4 v[214:217], v[236:237], off offset:192
	s_waitcnt vmcnt(18)
	v_pk_fma_f32 v[54:55], v[54:55], v[86:87], v[220:221]
	v_pk_fma_f32 v[52:53], v[52:53], v[84:85], v[218:219]
	global_store_dwordx4 v[232:233], v[52:55], off offset:128
	global_load_dwordx4 v[218:221], v[238:239], off
	s_waitcnt vmcnt(18)
	v_pk_fma_f32 v[50:51], v[50:51], v[78:79], v[224:225]
	v_pk_fma_f32 v[48:49], v[48:49], v[76:77], v[222:223]
	global_store_dwordx4 v[232:233], v[48:51], off offset:192
	global_load_dwordx4 v[222:225], v[238:239], off offset:64
	s_waitcnt vmcnt(18)
	v_pk_fma_f32 v[46:47], v[46:47], v[98:99], v[174:175]
	v_pk_fma_f32 v[44:45], v[44:45], v[96:97], v[172:173]
	global_store_dwordx4 v[234:235], v[44:47], off
	global_load_dwordx4 v[172:175], v[238:239], off offset:128
	s_waitcnt vmcnt(18)
	v_pk_fma_f32 v[42:43], v[42:43], v[90:91], v[192:193]
	v_pk_fma_f32 v[40:41], v[40:41], v[88:89], v[190:191]
	global_store_dwordx4 v[234:235], v[40:43], off offset:64
	global_load_dwordx4 v[190:193], v[238:239], off offset:192
	s_waitcnt vmcnt(18)
	v_pk_fma_f32 v[38:39], v[38:39], v[86:87], v[196:197]
	v_pk_fma_f32 v[36:37], v[36:37], v[84:85], v[194:195]
	global_store_dwordx4 v[234:235], v[36:39], off offset:128
	s_waitcnt vmcnt(17)
	v_pk_fma_f32 v[34:35], v[34:35], v[78:79], v[200:201]
	v_pk_fma_f32 v[32:33], v[32:33], v[76:77], v[198:199]
	global_store_dwordx4 v[234:235], v[32:35], off offset:192
	s_waitcnt vmcnt(16)
	v_pk_fma_f32 v[30:31], v[30:31], v[98:99], v[204:205]
	v_pk_fma_f32 v[28:29], v[28:29], v[96:97], v[202:203]
	global_store_dwordx4 v[236:237], v[28:31], off
	s_waitcnt vmcnt(15)
	v_pk_fma_f32 v[26:27], v[26:27], v[90:91], v[208:209]
	v_pk_fma_f32 v[24:25], v[24:25], v[88:89], v[206:207]
	global_store_dwordx4 v[236:237], v[24:27], off offset:64
	s_waitcnt vmcnt(14)
	v_pk_fma_f32 v[22:23], v[22:23], v[86:87], v[212:213]
	v_pk_fma_f32 v[20:21], v[20:21], v[84:85], v[210:211]
	global_store_dwordx4 v[236:237], v[20:23], off offset:128
	s_waitcnt vmcnt(13)
	v_pk_fma_f32 v[18:19], v[18:19], v[78:79], v[216:217]
	v_pk_fma_f32 v[16:17], v[16:17], v[76:77], v[214:215]
	global_store_dwordx4 v[236:237], v[16:19], off offset:192
	s_waitcnt vmcnt(12)
	v_pk_fma_f32 v[14:15], v[14:15], v[98:99], v[220:221]
	v_pk_fma_f32 v[12:13], v[12:13], v[96:97], v[218:219]
	global_store_dwordx4 v[238:239], v[12:15], off
	s_waitcnt vmcnt(11)
	v_pk_fma_f32 v[10:11], v[10:11], v[90:91], v[224:225]
	v_pk_fma_f32 v[8:9], v[8:9], v[88:89], v[222:223]
	global_store_dwordx4 v[238:239], v[8:11], off offset:64
	s_waitcnt vmcnt(10)
	v_pk_fma_f32 v[6:7], v[6:7], v[86:87], v[174:175]
	v_pk_fma_f32 v[4:5], v[4:5], v[84:85], v[172:173]
	global_store_dwordx4 v[238:239], v[4:7], off offset:128
	s_waitcnt vmcnt(9)
	v_pk_fma_f32 v[2:3], v[2:3], v[78:79], v[192:193]
	v_pk_fma_f32 v[0:1], v[0:1], v[76:77], v[190:191]
	global_store_dwordx4 v[238:239], v[0:3], off offset:192
	s_mov_b32 s0, 0xb0000
	s_mov_b64 s[0:1], -1
	s_and_b64 vcc, exec, s[40:41]
	s_cbranch_vccnz .LBB0_256
	s_andn2_b64 vcc, exec, s[10:11]
	s_cbranch_vccnz .LBB0_255
	s_barrier
	s_branch .LBB0_255

.Lst_entry:
	s_setprio 3
	s_mov_b32 s20, s52
	s_mov_b32 s21, s53
	s_add_i32 s2, s10, 0x23e10
	v_mov_b32_e32 v0, s2
	ds_read2_b32 v[0:1], v0 offset1:1
	v_mbcnt_lo_u32_b32 v142, -1, 0
	v_mbcnt_hi_u32_b32 v142, -1, v142
	v_mov_b32_e32 v185, 0
	v_mov_b32_e32 v187, 0
	s_waitcnt lgkmcnt(0)
	v_readfirstlane_b32 s56, v0
	v_readfirstlane_b32 s57, v1
	v_and_b32_e32 v143, 7, v142
	v_lshrrev_b32_e32 v144, 3, v142
	v_lshlrev_b32_e32 v145, 1, v144
	v_lshl_add_u32 v145, s6, 4, v145
	v_lshlrev_b32_e32 v182, 5, v143
	v_add_u32_e32 v140, s10, v182
	v_lshl_add_u32 v141, v145, 2, s10
	v_lshl_add_u32 v146, v144, 3, v143
	s_lshl_b32 s2, s6, 12
	s_add_i32 s2, s2, s10
	s_add_i32 s2, s2, 0xc700
	v_lshl_add_u32 v134, v146, 2, s2
	v_lshrrev_b32_e32 v146, 4, v142
	v_and_b32_e32 v147, 15, v142
	v_and_b32_e32 v148, 1, v147
	v_lshlrev_b32_e32 v148, 6, v148
	v_lshl_add_u32 v148, v146, 7, v148
	v_lshrrev_b32_e32 v180, 1, v147
	v_lshl_add_u32 v148, v180, 3, v148
	v_lshl_add_u32 v135, v148, 2, s2
	v_lshl_add_u32 v184, v145, 8, v182
	s_mov_b32 s70, 0

.Lst_chunk:
	v_add_u32_e32 v132, s75, v140
	v_add_u32_e32 v133, s75, v141
	ds_read_b128 v[40:43], v132 offset:256
	ds_read_b128 v[44:47], v132 offset:272
	ds_read_b128 v[48:51], v132 offset:512
	ds_read_b128 v[52:55], v132 offset:528
	ds_read_b128 v[56:59], v132 offset:768
	ds_read_b128 v[60:63], v132 offset:784
	ds_read_b128 v[64:67], v132 offset:1024
	ds_read_b128 v[68:71], v132 offset:1040
	ds_read_b64 v[72:73], v133 offset:1280
	ds_read_b128 v[74:77], v132 offset:1808
	ds_read_b128 v[78:81], v132 offset:1824
	ds_read_b128 v[82:85], v132 offset:2064
	ds_read_b128 v[86:89], v132 offset:2080
	ds_read_b128 v[90:93], v132 offset:2320
	ds_read_b128 v[94:97], v132 offset:2336
	ds_read_b128 v[98:101], v132 offset:2576
	ds_read_b128 v[102:105], v132 offset:2592
	ds_read_b64 v[106:107], v133 offset:2832
	s_waitcnt lgkmcnt(15)
	v_pk_mul_f32 v[32:33], v[0:1], v[40:41] op_sel_hi:[1,0]
	v_pk_mul_f32 v[34:35], v[2:3], v[40:41] op_sel:[0,1]
	v_pk_fma_f32 v[32:33], v[4:5], v[42:43], v[32:33] op_sel_hi:[1,0,1]
	v_pk_fma_f32 v[34:35], v[6:7], v[42:43], v[34:35] op_sel:[0,1,0]
	v_pk_fma_f32 v[32:33], v[8:9], v[44:45], v[32:33] op_sel_hi:[1,0,1]
	v_pk_fma_f32 v[34:35], v[10:11], v[44:45], v[34:35] op_sel:[0,1,0]
	v_pk_fma_f32 v[32:33], v[12:13], v[46:47], v[32:33] op_sel_hi:[1,0,1]
	v_pk_fma_f32 v[34:35], v[14:15], v[46:47], v[34:35] op_sel:[0,1,0]
	v_pk_add_f32 v[32:33], v[32:33], v[34:35]
	s_nop 1
	s_waitcnt lgkmcnt(9)
	v_add_f32_dpp v32, v32, v32 row_half_mirror row_mask:0xf bank_mask:0xf bound_ctrl:1
	v_add_f32_dpp v33, v33, v33 row_half_mirror row_mask:0xf bank_mask:0xf bound_ctrl:1
	v_pk_fma_f32 v[16:17], v[72:73], v[56:57], v[0:1] op_sel_hi:[1,0,1]
	v_add_f32_dpp v32, v32, v32 quad_perm:[1,0,3,2] row_mask:0xf bank_mask:0xf bound_ctrl:1
	v_add_f32_dpp v33, v33, v33 quad_perm:[1,0,3,2] row_mask:0xf bank_mask:0xf bound_ctrl:1
	v_pk_fma_f32 v[18:19], v[72:73], v[56:57], v[2:3] op_sel:[0,1,0]
	v_add_f32_dpp v32, v32, v32 quad_perm:[2,3,0,1] row_mask:0xf bank_mask:0xf bound_ctrl:1
	v_add_f32_dpp v33, v33, v33 quad_perm:[2,3,0,1] row_mask:0xf bank_mask:0xf bound_ctrl:1
	v_pk_fma_f32 v[20:21], v[72:73], v[58:59], v[4:5] op_sel_hi:[1,0,1]
	v_pk_fma_f32 v[22:23], v[72:73], v[58:59], v[6:7] op_sel:[0,1,0]
	v_pk_fma_f32 v[24:25], v[72:73], v[60:61], v[8:9] op_sel_hi:[1,0,1]
	v_pk_fma_f32 v[26:27], v[72:73], v[60:61], v[10:11] op_sel:[0,1,0]
	v_pk_fma_f32 v[28:29], v[72:73], v[62:63], v[12:13] op_sel_hi:[1,0,1]
	v_pk_fma_f32 v[30:31], v[72:73], v[62:63], v[14:15] op_sel:[0,1,0]
	v_pk_fma_f32 v[0:1], v[32:33], v[48:49], v[16:17] op_sel_hi:[1,0,1]
	v_pk_fma_f32 v[2:3], v[32:33], v[48:49], v[18:19] op_sel:[0,1,0]
	v_pk_fma_f32 v[4:5], v[32:33], v[50:51], v[20:21] op_sel_hi:[1,0,1]
	v_pk_fma_f32 v[6:7], v[32:33], v[50:51], v[22:23] op_sel:[0,1,0]
	v_pk_fma_f32 v[8:9], v[32:33], v[52:53], v[24:25] op_sel_hi:[1,0,1]
	v_pk_fma_f32 v[10:11], v[32:33], v[52:53], v[26:27] op_sel:[0,1,0]
	v_pk_fma_f32 v[12:13], v[32:33], v[54:55], v[28:29] op_sel_hi:[1,0,1]
	v_pk_fma_f32 v[14:15], v[32:33], v[54:55], v[30:31] op_sel:[0,1,0]
	s_waitcnt lgkmcnt(7)
	v_pk_mul_f32 v[32:33], v[0:1], v[74:75] op_sel_hi:[1,0]
	v_pk_mul_f32 v[36:37], v[0:1], v[64:65] op_sel_hi:[1,0]
	v_pk_mul_f32 v[34:35], v[2:3], v[74:75] op_sel:[0,1]
	v_pk_mul_f32 v[38:39], v[2:3], v[64:65] op_sel:[0,1]
	v_pk_fma_f32 v[32:33], v[4:5], v[76:77], v[32:33] op_sel_hi:[1,0,1]
	v_pk_fma_f32 v[36:37], v[4:5], v[66:67], v[36:37] op_sel_hi:[1,0,1]
	v_pk_fma_f32 v[34:35], v[6:7], v[76:77], v[34:35] op_sel:[0,1,0]
	v_pk_fma_f32 v[38:39], v[6:7], v[66:67], v[38:39] op_sel:[0,1,0]
	v_pk_fma_f32 v[32:33], v[8:9], v[78:79], v[32:33] op_sel_hi:[1,0,1]
	v_pk_fma_f32 v[36:37], v[8:9], v[68:69], v[36:37] op_sel_hi:[1,0,1]
	v_pk_fma_f32 v[34:35], v[10:11], v[78:79], v[34:35] op_sel:[0,1,0]
	v_pk_fma_f32 v[38:39], v[10:11], v[68:69], v[38:39] op_sel:[0,1,0]
	v_pk_fma_f32 v[32:33], v[12:13], v[80:81], v[32:33] op_sel_hi:[1,0,1]
	v_pk_fma_f32 v[36:37], v[12:13], v[70:71], v[36:37] op_sel_hi:[1,0,1]
	v_pk_fma_f32 v[34:35], v[14:15], v[80:81], v[34:35] op_sel:[0,1,0]
	v_pk_fma_f32 v[38:39], v[14:15], v[70:71], v[38:39] op_sel:[0,1,0]
	v_pk_add_f32 v[36:37], v[36:37], v[38:39]
	v_pk_add_f32 v[32:33], v[32:33], v[34:35]
	ds_write2st64_b32 v134, v36, v37 offset0:0 offset1:1
	ds_read_b128 v[40:43], v132 offset:3360
	ds_read_b128 v[44:47], v132 offset:3376
	ds_read_b128 v[48:51], v132 offset:3616
	ds_read_b128 v[52:55], v132 offset:3632
	ds_read_b128 v[56:59], v132 offset:3872
	ds_read_b128 v[60:63], v132 offset:3888
	ds_read_b128 v[64:67], v132 offset:4128
	ds_read_b128 v[68:71], v132 offset:4144
	ds_read_b64 v[72:73], v133 offset:4384
	s_waitcnt lgkmcnt(10)
	v_add_f32_dpp v32, v32, v32 row_half_mirror row_mask:0xf bank_mask:0xf bound_ctrl:1
	v_add_f32_dpp v33, v33, v33 row_half_mirror row_mask:0xf bank_mask:0xf bound_ctrl:1
	v_pk_fma_f32 v[16:17], v[106:107], v[90:91], v[0:1] op_sel_hi:[1,0,1]
	v_add_f32_dpp v32, v32, v32 quad_perm:[1,0,3,2] row_mask:0xf bank_mask:0xf bound_ctrl:1
	v_add_f32_dpp v33, v33, v33 quad_perm:[1,0,3,2] row_mask:0xf bank_mask:0xf bound_ctrl:1
	v_pk_fma_f32 v[18:19], v[106:107], v[90:91], v[2:3] op_sel:[0,1,0]
	v_add_f32_dpp v32, v32, v32 quad_perm:[2,3,0,1] row_mask:0xf bank_mask:0xf bound_ctrl:1
	v_add_f32_dpp v33, v33, v33 quad_perm:[2,3,0,1] row_mask:0xf bank_mask:0xf bound_ctrl:1
	v_pk_fma_f32 v[20:21], v[106:107], v[92:93], v[4:5] op_sel_hi:[1,0,1]
	v_pk_fma_f32 v[22:23], v[106:107], v[92:93], v[6:7] op_sel:[0,1,0]
	v_pk_fma_f32 v[24:25], v[106:107], v[94:95], v[8:9] op_sel_hi:[1,0,1]
	v_pk_fma_f32 v[26:27], v[106:107], v[94:95], v[10:11] op_sel:[0,1,0]
	v_pk_fma_f32 v[28:29], v[106:107], v[96:97], v[12:13] op_sel_hi:[1,0,1]
	v_pk_fma_f32 v[30:31], v[106:107], v[96:97], v[14:15] op_sel:[0,1,0]
	v_pk_fma_f32 v[0:1], v[32:33], v[82:83], v[16:17] op_sel_hi:[1,0,1]
	v_pk_fma_f32 v[2:3], v[32:33], v[82:83], v[18:19] op_sel:[0,1,0]
	v_pk_fma_f32 v[4:5], v[32:33], v[84:85], v[20:21] op_sel_hi:[1,0,1]
	v_pk_fma_f32 v[6:7], v[32:33], v[84:85], v[22:23] op_sel:[0,1,0]
	v_pk_fma_f32 v[8:9], v[32:33], v[86:87], v[24:25] op_sel_hi:[1,0,1]
	v_pk_fma_f32 v[10:11], v[32:33], v[86:87], v[26:27] op_sel:[0,1,0]
	v_pk_fma_f32 v[12:13], v[32:33], v[88:89], v[28:29] op_sel_hi:[1,0,1]
	v_pk_fma_f32 v[14:15], v[32:33], v[88:89], v[30:31] op_sel:[0,1,0]
	s_waitcnt lgkmcnt(7)
	v_pk_mul_f32 v[32:33], v[0:1], v[40:41] op_sel_hi:[1,0]
	v_pk_mul_f32 v[36:37], v[0:1], v[98:99] op_sel_hi:[1,0]
	v_pk_mul_f32 v[34:35], v[2:3], v[40:41] op_sel:[0,1]
	v_pk_mul_f32 v[38:39], v[2:3], v[98:99] op_sel:[0,1]
	v_pk_fma_f32 v[32:33], v[4:5], v[42:43], v[32:33] op_sel_hi:[1,0,1]
	v_pk_fma_f32 v[36:37], v[4:5], v[100:101], v[36:37] op_sel_hi:[1,0,1]
	v_pk_fma_f32 v[34:35], v[6:7], v[42:43], v[34:35] op_sel:[0,1,0]
	v_pk_fma_f32 v[38:39], v[6:7], v[100:101], v[38:39] op_sel:[0,1,0]
	v_pk_fma_f32 v[32:33], v[8:9], v[44:45], v[32:33] op_sel_hi:[1,0,1]
	v_pk_fma_f32 v[36:37], v[8:9], v[102:103], v[36:37] op_sel_hi:[1,0,1]
	v_pk_fma_f32 v[34:35], v[10:11], v[44:45], v[34:35] op_sel:[0,1,0]
	v_pk_fma_f32 v[38:39], v[10:11], v[102:103], v[38:39] op_sel:[0,1,0]
	v_pk_fma_f32 v[32:33], v[12:13], v[46:47], v[32:33] op_sel_hi:[1,0,1]
	v_pk_fma_f32 v[36:37], v[12:13], v[104:105], v[36:37] op_sel_hi:[1,0,1]
	v_pk_fma_f32 v[34:35], v[14:15], v[46:47], v[34:35] op_sel:[0,1,0]
	v_pk_fma_f32 v[38:39], v[14:15], v[104:105], v[38:39] op_sel:[0,1,0]
	v_pk_add_f32 v[36:37], v[36:37], v[38:39]
	v_pk_add_f32 v[32:33], v[32:33], v[34:35]
	ds_write2st64_b32 v134, v36, v37 offset0:2 offset1:3
	ds_read_b128 v[74:77], v132 offset:4912
	ds_read_b128 v[78:81], v132 offset:4928
	ds_read_b128 v[82:85], v132 offset:5168
	ds_read_b128 v[86:89], v132 offset:5184
	ds_read_b128 v[90:93], v132 offset:5424
	ds_read_b128 v[94:97], v132 offset:5440
	ds_read_b128 v[98:101], v132 offset:5680
	ds_read_b128 v[102:105], v132 offset:5696
	ds_read_b64 v[106:107], v133 offset:5936
	s_waitcnt lgkmcnt(10)
	v_add_f32_dpp v32, v32, v32 row_half_mirror row_mask:0xf bank_mask:0xf bound_ctrl:1
	v_add_f32_dpp v33, v33, v33 row_half_mirror row_mask:0xf bank_mask:0xf bound_ctrl:1
	v_pk_fma_f32 v[16:17], v[72:73], v[56:57], v[0:1] op_sel_hi:[1,0,1]
	v_add_f32_dpp v32, v32, v32 quad_perm:[1,0,3,2] row_mask:0xf bank_mask:0xf bound_ctrl:1
	v_add_f32_dpp v33, v33, v33 quad_perm:[1,0,3,2] row_mask:0xf bank_mask:0xf bound_ctrl:1
	v_pk_fma_f32 v[18:19], v[72:73], v[56:57], v[2:3] op_sel:[0,1,0]
	v_add_f32_dpp v32, v32, v32 quad_perm:[2,3,0,1] row_mask:0xf bank_mask:0xf bound_ctrl:1
	v_add_f32_dpp v33, v33, v33 quad_perm:[2,3,0,1] row_mask:0xf bank_mask:0xf bound_ctrl:1
	v_pk_fma_f32 v[20:21], v[72:73], v[58:59], v[4:5] op_sel_hi:[1,0,1]
	v_pk_fma_f32 v[22:23], v[72:73], v[58:59], v[6:7] op_sel:[0,1,0]
	v_pk_fma_f32 v[24:25], v[72:73], v[60:61], v[8:9] op_sel_hi:[1,0,1]
	v_pk_fma_f32 v[26:27], v[72:73], v[60:61], v[10:11] op_sel:[0,1,0]
	v_pk_fma_f32 v[28:29], v[72:73], v[62:63], v[12:13] op_sel_hi:[1,0,1]
	v_pk_fma_f32 v[30:31], v[72:73], v[62:63], v[14:15] op_sel:[0,1,0]
	v_pk_fma_f32 v[0:1], v[32:33], v[48:49], v[16:17] op_sel_hi:[1,0,1]
	v_pk_fma_f32 v[2:3], v[32:33], v[48:49], v[18:19] op_sel:[0,1,0]
	v_pk_fma_f32 v[4:5], v[32:33], v[50:51], v[20:21] op_sel_hi:[1,0,1]
	v_pk_fma_f32 v[6:7], v[32:33], v[50:51], v[22:23] op_sel:[0,1,0]
	v_pk_fma_f32 v[8:9], v[32:33], v[52:53], v[24:25] op_sel_hi:[1,0,1]
	v_pk_fma_f32 v[10:11], v[32:33], v[52:53], v[26:27] op_sel:[0,1,0]
	v_pk_fma_f32 v[12:13], v[32:33], v[54:55], v[28:29] op_sel_hi:[1,0,1]
	v_pk_fma_f32 v[14:15], v[32:33], v[54:55], v[30:31] op_sel:[0,1,0]
	s_waitcnt lgkmcnt(7)
	v_pk_mul_f32 v[32:33], v[0:1], v[74:75] op_sel_hi:[1,0]
	v_pk_mul_f32 v[36:37], v[0:1], v[64:65] op_sel_hi:[1,0]
	v_pk_mul_f32 v[34:35], v[2:3], v[74:75] op_sel:[0,1]
	v_pk_mul_f32 v[38:39], v[2:3], v[64:65] op_sel:[0,1]
	v_pk_fma_f32 v[32:33], v[4:5], v[76:77], v[32:33] op_sel_hi:[1,0,1]
	v_pk_fma_f32 v[36:37], v[4:5], v[66:67], v[36:37] op_sel_hi:[1,0,1]
	v_pk_fma_f32 v[34:35], v[6:7], v[76:77], v[34:35] op_sel:[0,1,0]
	v_pk_fma_f32 v[38:39], v[6:7], v[66:67], v[38:39] op_sel:[0,1,0]
	v_pk_fma_f32 v[32:33], v[8:9], v[78:79], v[32:33] op_sel_hi:[1,0,1]
	v_pk_fma_f32 v[36:37], v[8:9], v[68:69], v[36:37] op_sel_hi:[1,0,1]
	v_pk_fma_f32 v[34:35], v[10:11], v[78:79], v[34:35] op_sel:[0,1,0]
	v_pk_fma_f32 v[38:39], v[10:11], v[68:69], v[38:39] op_sel:[0,1,0]
	v_pk_fma_f32 v[32:33], v[12:13], v[80:81], v[32:33] op_sel_hi:[1,0,1]
	v_pk_fma_f32 v[36:37], v[12:13], v[70:71], v[36:37] op_sel_hi:[1,0,1]
	v_pk_fma_f32 v[34:35], v[14:15], v[80:81], v[34:35] op_sel:[0,1,0]
	v_pk_fma_f32 v[38:39], v[14:15], v[70:71], v[38:39] op_sel:[0,1,0]
	v_pk_add_f32 v[36:37], v[36:37], v[38:39]
	v_pk_add_f32 v[32:33], v[32:33], v[34:35]
	ds_write2st64_b32 v134, v36, v37 offset0:4 offset1:5
	ds_read_b128 v[40:43], v132 offset:6464
	ds_read_b128 v[44:47], v132 offset:6480
	ds_read_b128 v[48:51], v132 offset:6720
	ds_read_b128 v[52:55], v132 offset:6736
	ds_read_b128 v[56:59], v132 offset:6976
	ds_read_b128 v[60:63], v132 offset:6992
	ds_read_b128 v[64:67], v132 offset:7232
	ds_read_b128 v[68:71], v132 offset:7248
	ds_read_b64 v[72:73], v133 offset:7488
	s_waitcnt lgkmcnt(10)
	v_add_f32_dpp v32, v32, v32 row_half_mirror row_mask:0xf bank_mask:0xf bound_ctrl:1
	v_add_f32_dpp v33, v33, v33 row_half_mirror row_mask:0xf bank_mask:0xf bound_ctrl:1
	v_pk_fma_f32 v[16:17], v[106:107], v[90:91], v[0:1] op_sel_hi:[1,0,1]
	v_add_f32_dpp v32, v32, v32 quad_perm:[1,0,3,2] row_mask:0xf bank_mask:0xf bound_ctrl:1
	v_add_f32_dpp v33, v33, v33 quad_perm:[1,0,3,2] row_mask:0xf bank_mask:0xf bound_ctrl:1
	v_pk_fma_f32 v[18:19], v[106:107], v[90:91], v[2:3] op_sel:[0,1,0]
	v_add_f32_dpp v32, v32, v32 quad_perm:[2,3,0,1] row_mask:0xf bank_mask:0xf bound_ctrl:1
	v_add_f32_dpp v33, v33, v33 quad_perm:[2,3,0,1] row_mask:0xf bank_mask:0xf bound_ctrl:1
	v_pk_fma_f32 v[20:21], v[106:107], v[92:93], v[4:5] op_sel_hi:[1,0,1]
	v_pk_fma_f32 v[22:23], v[106:107], v[92:93], v[6:7] op_sel:[0,1,0]
	v_pk_fma_f32 v[24:25], v[106:107], v[94:95], v[8:9] op_sel_hi:[1,0,1]
	v_pk_fma_f32 v[26:27], v[106:107], v[94:95], v[10:11] op_sel:[0,1,0]
	v_pk_fma_f32 v[28:29], v[106:107], v[96:97], v[12:13] op_sel_hi:[1,0,1]
	v_pk_fma_f32 v[30:31], v[106:107], v[96:97], v[14:15] op_sel:[0,1,0]
	v_pk_fma_f32 v[0:1], v[32:33], v[82:83], v[16:17] op_sel_hi:[1,0,1]
	v_pk_fma_f32 v[2:3], v[32:33], v[82:83], v[18:19] op_sel:[0,1,0]
	v_pk_fma_f32 v[4:5], v[32:33], v[84:85], v[20:21] op_sel_hi:[1,0,1]
	v_pk_fma_f32 v[6:7], v[32:33], v[84:85], v[22:23] op_sel:[0,1,0]
	v_pk_fma_f32 v[8:9], v[32:33], v[86:87], v[24:25] op_sel_hi:[1,0,1]
	v_pk_fma_f32 v[10:11], v[32:33], v[86:87], v[26:27] op_sel:[0,1,0]
	v_pk_fma_f32 v[12:13], v[32:33], v[88:89], v[28:29] op_sel_hi:[1,0,1]
	v_pk_fma_f32 v[14:15], v[32:33], v[88:89], v[30:31] op_sel:[0,1,0]
	s_waitcnt lgkmcnt(7)
	v_pk_mul_f32 v[32:33], v[0:1], v[40:41] op_sel_hi:[1,0]
	v_pk_mul_f32 v[36:37], v[0:1], v[98:99] op_sel_hi:[1,0]
	v_pk_mul_f32 v[34:35], v[2:3], v[40:41] op_sel:[0,1]
	v_pk_mul_f32 v[38:39], v[2:3], v[98:99] op_sel:[0,1]
	v_pk_fma_f32 v[32:33], v[4:5], v[42:43], v[32:33] op_sel_hi:[1,0,1]
	v_pk_fma_f32 v[36:37], v[4:5], v[100:101], v[36:37] op_sel_hi:[1,0,1]
	v_pk_fma_f32 v[34:35], v[6:7], v[42:43], v[34:35] op_sel:[0,1,0]
	v_pk_fma_f32 v[38:39], v[6:7], v[100:101], v[38:39] op_sel:[0,1,0]
	v_pk_fma_f32 v[32:33], v[8:9], v[44:45], v[32:33] op_sel_hi:[1,0,1]
	v_pk_fma_f32 v[36:37], v[8:9], v[102:103], v[36:37] op_sel_hi:[1,0,1]
	v_pk_fma_f32 v[34:35], v[10:11], v[44:45], v[34:35] op_sel:[0,1,0]
	v_pk_fma_f32 v[38:39], v[10:11], v[102:103], v[38:39] op_sel:[0,1,0]
	v_pk_fma_f32 v[32:33], v[12:13], v[46:47], v[32:33] op_sel_hi:[1,0,1]
	v_pk_fma_f32 v[36:37], v[12:13], v[104:105], v[36:37] op_sel_hi:[1,0,1]
	v_pk_fma_f32 v[34:35], v[14:15], v[46:47], v[34:35] op_sel:[0,1,0]
	v_pk_fma_f32 v[38:39], v[14:15], v[104:105], v[38:39] op_sel:[0,1,0]
	v_pk_add_f32 v[36:37], v[36:37], v[38:39]
	v_pk_add_f32 v[32:33], v[32:33], v[34:35]
	ds_write2st64_b32 v134, v36, v37 offset0:6 offset1:7
	ds_read_b128 v[74:77], v132 offset:8016
	ds_read_b128 v[78:81], v132 offset:8032
	ds_read_b128 v[82:85], v132 offset:8272
	ds_read_b128 v[86:89], v132 offset:8288
	ds_read_b128 v[90:93], v132 offset:8528
	ds_read_b128 v[94:97], v132 offset:8544
	ds_read_b128 v[98:101], v132 offset:8784
	ds_read_b128 v[102:105], v132 offset:8800
	ds_read_b64 v[106:107], v133 offset:9040
	s_waitcnt lgkmcnt(10)
	v_add_f32_dpp v32, v32, v32 row_half_mirror row_mask:0xf bank_mask:0xf bound_ctrl:1
	v_add_f32_dpp v33, v33, v33 row_half_mirror row_mask:0xf bank_mask:0xf bound_ctrl:1
	v_pk_fma_f32 v[16:17], v[72:73], v[56:57], v[0:1] op_sel_hi:[1,0,1]
	v_add_f32_dpp v32, v32, v32 quad_perm:[1,0,3,2] row_mask:0xf bank_mask:0xf bound_ctrl:1
	v_add_f32_dpp v33, v33, v33 quad_perm:[1,0,3,2] row_mask:0xf bank_mask:0xf bound_ctrl:1
	v_pk_fma_f32 v[18:19], v[72:73], v[56:57], v[2:3] op_sel:[0,1,0]
	v_add_f32_dpp v32, v32, v32 quad_perm:[2,3,0,1] row_mask:0xf bank_mask:0xf bound_ctrl:1
	v_add_f32_dpp v33, v33, v33 quad_perm:[2,3,0,1] row_mask:0xf bank_mask:0xf bound_ctrl:1
	v_pk_fma_f32 v[20:21], v[72:73], v[58:59], v[4:5] op_sel_hi:[1,0,1]
	v_pk_fma_f32 v[22:23], v[72:73], v[58:59], v[6:7] op_sel:[0,1,0]
	v_pk_fma_f32 v[24:25], v[72:73], v[60:61], v[8:9] op_sel_hi:[1,0,1]
	v_pk_fma_f32 v[26:27], v[72:73], v[60:61], v[10:11] op_sel:[0,1,0]
	v_pk_fma_f32 v[28:29], v[72:73], v[62:63], v[12:13] op_sel_hi:[1,0,1]
	v_pk_fma_f32 v[30:31], v[72:73], v[62:63], v[14:15] op_sel:[0,1,0]
	v_pk_fma_f32 v[0:1], v[32:33], v[48:49], v[16:17] op_sel_hi:[1,0,1]
	v_pk_fma_f32 v[2:3], v[32:33], v[48:49], v[18:19] op_sel:[0,1,0]
	v_pk_fma_f32 v[4:5], v[32:33], v[50:51], v[20:21] op_sel_hi:[1,0,1]
	v_pk_fma_f32 v[6:7], v[32:33], v[50:51], v[22:23] op_sel:[0,1,0]
	v_pk_fma_f32 v[8:9], v[32:33], v[52:53], v[24:25] op_sel_hi:[1,0,1]
	v_pk_fma_f32 v[10:11], v[32:33], v[52:53], v[26:27] op_sel:[0,1,0]
	v_pk_fma_f32 v[12:13], v[32:33], v[54:55], v[28:29] op_sel_hi:[1,0,1]
	v_pk_fma_f32 v[14:15], v[32:33], v[54:55], v[30:31] op_sel:[0,1,0]
	s_waitcnt lgkmcnt(7)
	v_pk_mul_f32 v[32:33], v[0:1], v[74:75] op_sel_hi:[1,0]
	v_pk_mul_f32 v[36:37], v[0:1], v[64:65] op_sel_hi:[1,0]
	v_pk_mul_f32 v[34:35], v[2:3], v[74:75] op_sel:[0,1]
	v_pk_mul_f32 v[38:39], v[2:3], v[64:65] op_sel:[0,1]
	v_pk_fma_f32 v[32:33], v[4:5], v[76:77], v[32:33] op_sel_hi:[1,0,1]
	v_pk_fma_f32 v[36:37], v[4:5], v[66:67], v[36:37] op_sel_hi:[1,0,1]
	v_pk_fma_f32 v[34:35], v[6:7], v[76:77], v[34:35] op_sel:[0,1,0]
	v_pk_fma_f32 v[38:39], v[6:7], v[66:67], v[38:39] op_sel:[0,1,0]
	v_pk_fma_f32 v[32:33], v[8:9], v[78:79], v[32:33] op_sel_hi:[1,0,1]
	v_pk_fma_f32 v[36:37], v[8:9], v[68:69], v[36:37] op_sel_hi:[1,0,1]
	v_pk_fma_f32 v[34:35], v[10:11], v[78:79], v[34:35] op_sel:[0,1,0]
	v_pk_fma_f32 v[38:39], v[10:11], v[68:69], v[38:39] op_sel:[0,1,0]
	v_pk_fma_f32 v[32:33], v[12:13], v[80:81], v[32:33] op_sel_hi:[1,0,1]
	v_pk_fma_f32 v[36:37], v[12:13], v[70:71], v[36:37] op_sel_hi:[1,0,1]
	v_pk_fma_f32 v[34:35], v[14:15], v[80:81], v[34:35] op_sel:[0,1,0]
	v_pk_fma_f32 v[38:39], v[14:15], v[70:71], v[38:39] op_sel:[0,1,0]
	v_pk_add_f32 v[36:37], v[36:37], v[38:39]
	v_pk_add_f32 v[32:33], v[32:33], v[34:35]
	ds_write2st64_b32 v134, v36, v37 offset0:8 offset1:9
	ds_read_b128 v[40:43], v132 offset:9568
	ds_read_b128 v[44:47], v132 offset:9584
	ds_read_b128 v[48:51], v132 offset:9824
	ds_read_b128 v[52:55], v132 offset:9840
	ds_read_b128 v[56:59], v132 offset:10080
	ds_read_b128 v[60:63], v132 offset:10096
	ds_read_b128 v[64:67], v132 offset:10336
	ds_read_b128 v[68:71], v132 offset:10352
	ds_read_b64 v[72:73], v133 offset:10592
	s_waitcnt lgkmcnt(10)
	v_add_f32_dpp v32, v32, v32 row_half_mirror row_mask:0xf bank_mask:0xf bound_ctrl:1
	v_add_f32_dpp v33, v33, v33 row_half_mirror row_mask:0xf bank_mask:0xf bound_ctrl:1
	v_pk_fma_f32 v[16:17], v[106:107], v[90:91], v[0:1] op_sel_hi:[1,0,1]
	v_add_f32_dpp v32, v32, v32 quad_perm:[1,0,3,2] row_mask:0xf bank_mask:0xf bound_ctrl:1
	v_add_f32_dpp v33, v33, v33 quad_perm:[1,0,3,2] row_mask:0xf bank_mask:0xf bound_ctrl:1
	v_pk_fma_f32 v[18:19], v[106:107], v[90:91], v[2:3] op_sel:[0,1,0]
	v_add_f32_dpp v32, v32, v32 quad_perm:[2,3,0,1] row_mask:0xf bank_mask:0xf bound_ctrl:1
	v_add_f32_dpp v33, v33, v33 quad_perm:[2,3,0,1] row_mask:0xf bank_mask:0xf bound_ctrl:1
	v_pk_fma_f32 v[20:21], v[106:107], v[92:93], v[4:5] op_sel_hi:[1,0,1]
	v_pk_fma_f32 v[22:23], v[106:107], v[92:93], v[6:7] op_sel:[0,1,0]
	v_pk_fma_f32 v[24:25], v[106:107], v[94:95], v[8:9] op_sel_hi:[1,0,1]
	v_pk_fma_f32 v[26:27], v[106:107], v[94:95], v[10:11] op_sel:[0,1,0]
	v_pk_fma_f32 v[28:29], v[106:107], v[96:97], v[12:13] op_sel_hi:[1,0,1]
	v_pk_fma_f32 v[30:31], v[106:107], v[96:97], v[14:15] op_sel:[0,1,0]
	v_pk_fma_f32 v[0:1], v[32:33], v[82:83], v[16:17] op_sel_hi:[1,0,1]
	v_pk_fma_f32 v[2:3], v[32:33], v[82:83], v[18:19] op_sel:[0,1,0]
	v_pk_fma_f32 v[4:5], v[32:33], v[84:85], v[20:21] op_sel_hi:[1,0,1]
	v_pk_fma_f32 v[6:7], v[32:33], v[84:85], v[22:23] op_sel:[0,1,0]
	v_pk_fma_f32 v[8:9], v[32:33], v[86:87], v[24:25] op_sel_hi:[1,0,1]
	v_pk_fma_f32 v[10:11], v[32:33], v[86:87], v[26:27] op_sel:[0,1,0]
	v_pk_fma_f32 v[12:13], v[32:33], v[88:89], v[28:29] op_sel_hi:[1,0,1]
	v_pk_fma_f32 v[14:15], v[32:33], v[88:89], v[30:31] op_sel:[0,1,0]
	s_waitcnt lgkmcnt(7)
	v_pk_mul_f32 v[32:33], v[0:1], v[40:41] op_sel_hi:[1,0]
	v_pk_mul_f32 v[36:37], v[0:1], v[98:99] op_sel_hi:[1,0]
	v_pk_mul_f32 v[34:35], v[2:3], v[40:41] op_sel:[0,1]
	v_pk_mul_f32 v[38:39], v[2:3], v[98:99] op_sel:[0,1]
	v_pk_fma_f32 v[32:33], v[4:5], v[42:43], v[32:33] op_sel_hi:[1,0,1]
	v_pk_fma_f32 v[36:37], v[4:5], v[100:101], v[36:37] op_sel_hi:[1,0,1]
	v_pk_fma_f32 v[34:35], v[6:7], v[42:43], v[34:35] op_sel:[0,1,0]
	v_pk_fma_f32 v[38:39], v[6:7], v[100:101], v[38:39] op_sel:[0,1,0]
	v_pk_fma_f32 v[32:33], v[8:9], v[44:45], v[32:33] op_sel_hi:[1,0,1]
	v_pk_fma_f32 v[36:37], v[8:9], v[102:103], v[36:37] op_sel_hi:[1,0,1]
	v_pk_fma_f32 v[34:35], v[10:11], v[44:45], v[34:35] op_sel:[0,1,0]
	v_pk_fma_f32 v[38:39], v[10:11], v[102:103], v[38:39] op_sel:[0,1,0]
	v_pk_fma_f32 v[32:33], v[12:13], v[46:47], v[32:33] op_sel_hi:[1,0,1]
	v_pk_fma_f32 v[36:37], v[12:13], v[104:105], v[36:37] op_sel_hi:[1,0,1]
	v_pk_fma_f32 v[34:35], v[14:15], v[46:47], v[34:35] op_sel:[0,1,0]
	v_pk_fma_f32 v[38:39], v[14:15], v[104:105], v[38:39] op_sel:[0,1,0]
	v_pk_add_f32 v[36:37], v[36:37], v[38:39]
	v_pk_add_f32 v[32:33], v[32:33], v[34:35]
	ds_write2st64_b32 v134, v36, v37 offset0:10 offset1:11
	ds_read_b128 v[74:77], v132 offset:11120
	ds_read_b128 v[78:81], v132 offset:11136
	ds_read_b128 v[82:85], v132 offset:11376
	ds_read_b128 v[86:89], v132 offset:11392
	ds_read_b128 v[90:93], v132 offset:11632
	ds_read_b128 v[94:97], v132 offset:11648
	ds_read_b128 v[98:101], v132 offset:11888
	ds_read_b128 v[102:105], v132 offset:11904
	ds_read_b64 v[106:107], v133 offset:12144
	s_waitcnt lgkmcnt(10)
	v_add_f32_dpp v32, v32, v32 row_half_mirror row_mask:0xf bank_mask:0xf bound_ctrl:1
	v_add_f32_dpp v33, v33, v33 row_half_mirror row_mask:0xf bank_mask:0xf bound_ctrl:1
	v_pk_fma_f32 v[16:17], v[72:73], v[56:57], v[0:1] op_sel_hi:[1,0,1]
	v_add_f32_dpp v32, v32, v32 quad_perm:[1,0,3,2] row_mask:0xf bank_mask:0xf bound_ctrl:1
	v_add_f32_dpp v33, v33, v33 quad_perm:[1,0,3,2] row_mask:0xf bank_mask:0xf bound_ctrl:1
	v_pk_fma_f32 v[18:19], v[72:73], v[56:57], v[2:3] op_sel:[0,1,0]
	v_add_f32_dpp v32, v32, v32 quad_perm:[2,3,0,1] row_mask:0xf bank_mask:0xf bound_ctrl:1
	v_add_f32_dpp v33, v33, v33 quad_perm:[2,3,0,1] row_mask:0xf bank_mask:0xf bound_ctrl:1
	v_pk_fma_f32 v[20:21], v[72:73], v[58:59], v[4:5] op_sel_hi:[1,0,1]
	v_pk_fma_f32 v[22:23], v[72:73], v[58:59], v[6:7] op_sel:[0,1,0]
	v_pk_fma_f32 v[24:25], v[72:73], v[60:61], v[8:9] op_sel_hi:[1,0,1]
	v_pk_fma_f32 v[26:27], v[72:73], v[60:61], v[10:11] op_sel:[0,1,0]
	v_pk_fma_f32 v[28:29], v[72:73], v[62:63], v[12:13] op_sel_hi:[1,0,1]
	v_pk_fma_f32 v[30:31], v[72:73], v[62:63], v[14:15] op_sel:[0,1,0]
	v_pk_fma_f32 v[0:1], v[32:33], v[48:49], v[16:17] op_sel_hi:[1,0,1]
	v_pk_fma_f32 v[2:3], v[32:33], v[48:49], v[18:19] op_sel:[0,1,0]
	v_pk_fma_f32 v[4:5], v[32:33], v[50:51], v[20:21] op_sel_hi:[1,0,1]
	v_pk_fma_f32 v[6:7], v[32:33], v[50:51], v[22:23] op_sel:[0,1,0]
	v_pk_fma_f32 v[8:9], v[32:33], v[52:53], v[24:25] op_sel_hi:[1,0,1]
	v_pk_fma_f32 v[10:11], v[32:33], v[52:53], v[26:27] op_sel:[0,1,0]
	v_pk_fma_f32 v[12:13], v[32:33], v[54:55], v[28:29] op_sel_hi:[1,0,1]
	v_pk_fma_f32 v[14:15], v[32:33], v[54:55], v[30:31] op_sel:[0,1,0]
	s_waitcnt lgkmcnt(7)
	v_pk_mul_f32 v[32:33], v[0:1], v[74:75] op_sel_hi:[1,0]
	v_pk_mul_f32 v[36:37], v[0:1], v[64:65] op_sel_hi:[1,0]
	v_pk_mul_f32 v[34:35], v[2:3], v[74:75] op_sel:[0,1]
	v_pk_mul_f32 v[38:39], v[2:3], v[64:65] op_sel:[0,1]
	v_pk_fma_f32 v[32:33], v[4:5], v[76:77], v[32:33] op_sel_hi:[1,0,1]
	v_pk_fma_f32 v[36:37], v[4:5], v[66:67], v[36:37] op_sel_hi:[1,0,1]
	v_pk_fma_f32 v[34:35], v[6:7], v[76:77], v[34:35] op_sel:[0,1,0]
	v_pk_fma_f32 v[38:39], v[6:7], v[66:67], v[38:39] op_sel:[0,1,0]
	v_pk_fma_f32 v[32:33], v[8:9], v[78:79], v[32:33] op_sel_hi:[1,0,1]
	v_pk_fma_f32 v[36:37], v[8:9], v[68:69], v[36:37] op_sel_hi:[1,0,1]
	v_pk_fma_f32 v[34:35], v[10:11], v[78:79], v[34:35] op_sel:[0,1,0]
	v_pk_fma_f32 v[38:39], v[10:11], v[68:69], v[38:39] op_sel:[0,1,0]
	v_pk_fma_f32 v[32:33], v[12:13], v[80:81], v[32:33] op_sel_hi:[1,0,1]
	v_pk_fma_f32 v[36:37], v[12:13], v[70:71], v[36:37] op_sel_hi:[1,0,1]
	v_pk_fma_f32 v[34:35], v[14:15], v[80:81], v[34:35] op_sel:[0,1,0]
	v_pk_fma_f32 v[38:39], v[14:15], v[70:71], v[38:39] op_sel:[0,1,0]
	v_pk_add_f32 v[36:37], v[36:37], v[38:39]
	v_pk_add_f32 v[32:33], v[32:33], v[34:35]
	ds_write2st64_b32 v134, v36, v37 offset0:12 offset1:13
	ds_read_b128 v[40:43], v132 offset:12672
	ds_read_b128 v[44:47], v132 offset:12688
	ds_read_b128 v[48:51], v132 offset:12928
	ds_read_b128 v[52:55], v132 offset:12944
	ds_read_b128 v[56:59], v132 offset:13184
	ds_read_b128 v[60:63], v132 offset:13200
	ds_read_b128 v[64:67], v132 offset:13440
	ds_read_b128 v[68:71], v132 offset:13456
	ds_read_b64 v[72:73], v133 offset:13696
	s_waitcnt lgkmcnt(10)
	v_add_f32_dpp v32, v32, v32 row_half_mirror row_mask:0xf bank_mask:0xf bound_ctrl:1
	v_add_f32_dpp v33, v33, v33 row_half_mirror row_mask:0xf bank_mask:0xf bound_ctrl:1
	v_pk_fma_f32 v[16:17], v[106:107], v[90:91], v[0:1] op_sel_hi:[1,0,1]
	v_add_f32_dpp v32, v32, v32 quad_perm:[1,0,3,2] row_mask:0xf bank_mask:0xf bound_ctrl:1
	v_add_f32_dpp v33, v33, v33 quad_perm:[1,0,3,2] row_mask:0xf bank_mask:0xf bound_ctrl:1
	v_pk_fma_f32 v[18:19], v[106:107], v[90:91], v[2:3] op_sel:[0,1,0]
	v_add_f32_dpp v32, v32, v32 quad_perm:[2,3,0,1] row_mask:0xf bank_mask:0xf bound_ctrl:1
	v_add_f32_dpp v33, v33, v33 quad_perm:[2,3,0,1] row_mask:0xf bank_mask:0xf bound_ctrl:1
	v_pk_fma_f32 v[20:21], v[106:107], v[92:93], v[4:5] op_sel_hi:[1,0,1]
	v_pk_fma_f32 v[22:23], v[106:107], v[92:93], v[6:7] op_sel:[0,1,0]
	v_pk_fma_f32 v[24:25], v[106:107], v[94:95], v[8:9] op_sel_hi:[1,0,1]
	v_pk_fma_f32 v[26:27], v[106:107], v[94:95], v[10:11] op_sel:[0,1,0]
	v_pk_fma_f32 v[28:29], v[106:107], v[96:97], v[12:13] op_sel_hi:[1,0,1]
	v_pk_fma_f32 v[30:31], v[106:107], v[96:97], v[14:15] op_sel:[0,1,0]
	v_pk_fma_f32 v[0:1], v[32:33], v[82:83], v[16:17] op_sel_hi:[1,0,1]
	v_pk_fma_f32 v[2:3], v[32:33], v[82:83], v[18:19] op_sel:[0,1,0]
	v_pk_fma_f32 v[4:5], v[32:33], v[84:85], v[20:21] op_sel_hi:[1,0,1]
	v_pk_fma_f32 v[6:7], v[32:33], v[84:85], v[22:23] op_sel:[0,1,0]
	v_pk_fma_f32 v[8:9], v[32:33], v[86:87], v[24:25] op_sel_hi:[1,0,1]
	v_pk_fma_f32 v[10:11], v[32:33], v[86:87], v[26:27] op_sel:[0,1,0]
	v_pk_fma_f32 v[12:13], v[32:33], v[88:89], v[28:29] op_sel_hi:[1,0,1]
	v_pk_fma_f32 v[14:15], v[32:33], v[88:89], v[30:31] op_sel:[0,1,0]
	s_waitcnt lgkmcnt(7)
	v_pk_mul_f32 v[32:33], v[0:1], v[40:41] op_sel_hi:[1,0]
	v_pk_mul_f32 v[36:37], v[0:1], v[98:99] op_sel_hi:[1,0]
	v_pk_mul_f32 v[34:35], v[2:3], v[40:41] op_sel:[0,1]
	v_pk_mul_f32 v[38:39], v[2:3], v[98:99] op_sel:[0,1]
	v_pk_fma_f32 v[32:33], v[4:5], v[42:43], v[32:33] op_sel_hi:[1,0,1]
	v_pk_fma_f32 v[36:37], v[4:5], v[100:101], v[36:37] op_sel_hi:[1,0,1]
	v_pk_fma_f32 v[34:35], v[6:7], v[42:43], v[34:35] op_sel:[0,1,0]
	v_pk_fma_f32 v[38:39], v[6:7], v[100:101], v[38:39] op_sel:[0,1,0]
	v_pk_fma_f32 v[32:33], v[8:9], v[44:45], v[32:33] op_sel_hi:[1,0,1]
	v_pk_fma_f32 v[36:37], v[8:9], v[102:103], v[36:37] op_sel_hi:[1,0,1]
	v_pk_fma_f32 v[34:35], v[10:11], v[44:45], v[34:35] op_sel:[0,1,0]
	v_pk_fma_f32 v[38:39], v[10:11], v[102:103], v[38:39] op_sel:[0,1,0]
	v_pk_fma_f32 v[32:33], v[12:13], v[46:47], v[32:33] op_sel_hi:[1,0,1]
	v_pk_fma_f32 v[36:37], v[12:13], v[104:105], v[36:37] op_sel_hi:[1,0,1]
	v_pk_fma_f32 v[34:35], v[14:15], v[46:47], v[34:35] op_sel:[0,1,0]
	v_pk_fma_f32 v[38:39], v[14:15], v[104:105], v[38:39] op_sel:[0,1,0]
	v_pk_add_f32 v[36:37], v[36:37], v[38:39]
	v_pk_add_f32 v[32:33], v[32:33], v[34:35]
	ds_write2st64_b32 v134, v36, v37 offset0:14 offset1:15
	ds_read_b128 v[74:77], v132 offset:14224
	ds_read_b128 v[78:81], v132 offset:14240
	ds_read_b128 v[82:85], v132 offset:14480
	ds_read_b128 v[86:89], v132 offset:14496
	ds_read_b128 v[90:93], v132 offset:14736
	ds_read_b128 v[94:97], v132 offset:14752
	ds_read_b128 v[98:101], v132 offset:14992
	ds_read_b128 v[102:105], v132 offset:15008
	ds_read_b64 v[106:107], v133 offset:15248
	ds_read_b128 v[116:119], v135
	ds_read_b128 v[120:123], v135 offset:16
	ds_read_b128 v[124:127], v135 offset:2048
	ds_read_b128 v[128:131], v135 offset:2064
	s_waitcnt lgkmcnt(2)
	v_pk_add_f32 v[116:117], v[116:117], v[118:119]
	v_pk_add_f32 v[120:121], v[120:121], v[122:123]
	s_waitcnt lgkmcnt(0)
	v_pk_add_f32 v[124:125], v[124:125], v[126:127]
	v_pk_add_f32 v[128:129], v[128:129], v[130:131]
	v_pk_add_f32 v[116:117], v[116:117], v[120:121]
	v_pk_add_f32 v[124:125], v[124:125], v[128:129]
	v_add_f32_e32 v116, v116, v117
	v_add_f32_e32 v124, v124, v125
	global_atomic_add_f32 v[136:137], v116, off
	global_atomic_add_f32 v[138:139], v124, off
	v_lshl_add_u64 v[136:137], v[136:137], 0, s[38:39]
	v_lshl_add_u64 v[138:139], v[138:139], 0, s[38:39]
	s_waitcnt lgkmcnt(10)
	v_add_f32_dpp v32, v32, v32 row_half_mirror row_mask:0xf bank_mask:0xf bound_ctrl:1
	v_add_f32_dpp v33, v33, v33 row_half_mirror row_mask:0xf bank_mask:0xf bound_ctrl:1
	v_pk_fma_f32 v[16:17], v[72:73], v[56:57], v[0:1] op_sel_hi:[1,0,1]
	v_add_f32_dpp v32, v32, v32 quad_perm:[1,0,3,2] row_mask:0xf bank_mask:0xf bound_ctrl:1
	v_add_f32_dpp v33, v33, v33 quad_perm:[1,0,3,2] row_mask:0xf bank_mask:0xf bound_ctrl:1
	v_pk_fma_f32 v[18:19], v[72:73], v[56:57], v[2:3] op_sel:[0,1,0]
	v_add_f32_dpp v32, v32, v32 quad_perm:[2,3,0,1] row_mask:0xf bank_mask:0xf bound_ctrl:1
	v_add_f32_dpp v33, v33, v33 quad_perm:[2,3,0,1] row_mask:0xf bank_mask:0xf bound_ctrl:1
	v_pk_fma_f32 v[20:21], v[72:73], v[58:59], v[4:5] op_sel_hi:[1,0,1]
	v_pk_fma_f32 v[22:23], v[72:73], v[58:59], v[6:7] op_sel:[0,1,0]
	v_pk_fma_f32 v[24:25], v[72:73], v[60:61], v[8:9] op_sel_hi:[1,0,1]
	v_pk_fma_f32 v[26:27], v[72:73], v[60:61], v[10:11] op_sel:[0,1,0]
	v_pk_fma_f32 v[28:29], v[72:73], v[62:63], v[12:13] op_sel_hi:[1,0,1]
	v_pk_fma_f32 v[30:31], v[72:73], v[62:63], v[14:15] op_sel:[0,1,0]
	v_pk_fma_f32 v[0:1], v[32:33], v[48:49], v[16:17] op_sel_hi:[1,0,1]
	v_pk_fma_f32 v[2:3], v[32:33], v[48:49], v[18:19] op_sel:[0,1,0]
	v_pk_fma_f32 v[4:5], v[32:33], v[50:51], v[20:21] op_sel_hi:[1,0,1]
	v_pk_fma_f32 v[6:7], v[32:33], v[50:51], v[22:23] op_sel:[0,1,0]
	v_pk_fma_f32 v[8:9], v[32:33], v[52:53], v[24:25] op_sel_hi:[1,0,1]
	v_pk_fma_f32 v[10:11], v[32:33], v[52:53], v[26:27] op_sel:[0,1,0]
	v_pk_fma_f32 v[12:13], v[32:33], v[54:55], v[28:29] op_sel_hi:[1,0,1]
	v_pk_fma_f32 v[14:15], v[32:33], v[54:55], v[30:31] op_sel:[0,1,0]
	s_waitcnt lgkmcnt(7)
	v_pk_mul_f32 v[32:33], v[0:1], v[74:75] op_sel_hi:[1,0]
	v_pk_mul_f32 v[36:37], v[0:1], v[64:65] op_sel_hi:[1,0]
	v_pk_mul_f32 v[34:35], v[2:3], v[74:75] op_sel:[0,1]
	v_pk_mul_f32 v[38:39], v[2:3], v[64:65] op_sel:[0,1]
	v_pk_fma_f32 v[32:33], v[4:5], v[76:77], v[32:33] op_sel_hi:[1,0,1]
	v_pk_fma_f32 v[36:37], v[4:5], v[66:67], v[36:37] op_sel_hi:[1,0,1]
	v_pk_fma_f32 v[34:35], v[6:7], v[76:77], v[34:35] op_sel:[0,1,0]
	v_pk_fma_f32 v[38:39], v[6:7], v[66:67], v[38:39] op_sel:[0,1,0]
	v_pk_fma_f32 v[32:33], v[8:9], v[78:79], v[32:33] op_sel_hi:[1,0,1]
	v_pk_fma_f32 v[36:37], v[8:9], v[68:69], v[36:37] op_sel_hi:[1,0,1]
	v_pk_fma_f32 v[34:35], v[10:11], v[78:79], v[34:35] op_sel:[0,1,0]
	v_pk_fma_f32 v[38:39], v[10:11], v[68:69], v[38:39] op_sel:[0,1,0]
	v_pk_fma_f32 v[32:33], v[12:13], v[80:81], v[32:33] op_sel_hi:[1,0,1]
	v_pk_fma_f32 v[36:37], v[12:13], v[70:71], v[36:37] op_sel_hi:[1,0,1]
	v_pk_fma_f32 v[34:35], v[14:15], v[80:81], v[34:35] op_sel:[0,1,0]
	v_pk_fma_f32 v[38:39], v[14:15], v[70:71], v[38:39] op_sel:[0,1,0]
	v_pk_add_f32 v[36:37], v[36:37], v[38:39]
	v_pk_add_f32 v[32:33], v[32:33], v[34:35]
	ds_write2st64_b32 v134, v36, v37 offset0:0 offset1:1
	ds_read_b128 v[40:43], v132 offset:15776
	ds_read_b128 v[44:47], v132 offset:15792
	ds_read_b128 v[48:51], v132 offset:16032
	ds_read_b128 v[52:55], v132 offset:16048
	ds_read_b128 v[56:59], v132 offset:16288
	ds_read_b128 v[60:63], v132 offset:16304
	ds_read_b128 v[64:67], v132 offset:16544
	ds_read_b128 v[68:71], v132 offset:16560
	ds_read_b64 v[72:73], v133 offset:16800
	s_waitcnt lgkmcnt(10)
	v_add_f32_dpp v32, v32, v32 row_half_mirror row_mask:0xf bank_mask:0xf bound_ctrl:1
	v_add_f32_dpp v33, v33, v33 row_half_mirror row_mask:0xf bank_mask:0xf bound_ctrl:1
	v_pk_fma_f32 v[16:17], v[106:107], v[90:91], v[0:1] op_sel_hi:[1,0,1]
	v_add_f32_dpp v32, v32, v32 quad_perm:[1,0,3,2] row_mask:0xf bank_mask:0xf bound_ctrl:1
	v_add_f32_dpp v33, v33, v33 quad_perm:[1,0,3,2] row_mask:0xf bank_mask:0xf bound_ctrl:1
	v_pk_fma_f32 v[18:19], v[106:107], v[90:91], v[2:3] op_sel:[0,1,0]
	v_add_f32_dpp v32, v32, v32 quad_perm:[2,3,0,1] row_mask:0xf bank_mask:0xf bound_ctrl:1
	v_add_f32_dpp v33, v33, v33 quad_perm:[2,3,0,1] row_mask:0xf bank_mask:0xf bound_ctrl:1
	v_pk_fma_f32 v[20:21], v[106:107], v[92:93], v[4:5] op_sel_hi:[1,0,1]
	v_pk_fma_f32 v[22:23], v[106:107], v[92:93], v[6:7] op_sel:[0,1,0]
	v_pk_fma_f32 v[24:25], v[106:107], v[94:95], v[8:9] op_sel_hi:[1,0,1]
	v_pk_fma_f32 v[26:27], v[106:107], v[94:95], v[10:11] op_sel:[0,1,0]
	v_pk_fma_f32 v[28:29], v[106:107], v[96:97], v[12:13] op_sel_hi:[1,0,1]
	v_pk_fma_f32 v[30:31], v[106:107], v[96:97], v[14:15] op_sel:[0,1,0]
	v_pk_fma_f32 v[0:1], v[32:33], v[82:83], v[16:17] op_sel_hi:[1,0,1]
	v_pk_fma_f32 v[2:3], v[32:33], v[82:83], v[18:19] op_sel:[0,1,0]
	v_pk_fma_f32 v[4:5], v[32:33], v[84:85], v[20:21] op_sel_hi:[1,0,1]
	v_pk_fma_f32 v[6:7], v[32:33], v[84:85], v[22:23] op_sel:[0,1,0]
	v_pk_fma_f32 v[8:9], v[32:33], v[86:87], v[24:25] op_sel_hi:[1,0,1]
	v_pk_fma_f32 v[10:11], v[32:33], v[86:87], v[26:27] op_sel:[0,1,0]
	v_pk_fma_f32 v[12:13], v[32:33], v[88:89], v[28:29] op_sel_hi:[1,0,1]
	v_pk_fma_f32 v[14:15], v[32:33], v[88:89], v[30:31] op_sel:[0,1,0]
	s_waitcnt lgkmcnt(7)
	v_pk_mul_f32 v[32:33], v[0:1], v[40:41] op_sel_hi:[1,0]
	v_pk_mul_f32 v[36:37], v[0:1], v[98:99] op_sel_hi:[1,0]
	v_pk_mul_f32 v[34:35], v[2:3], v[40:41] op_sel:[0,1]
	v_pk_mul_f32 v[38:39], v[2:3], v[98:99] op_sel:[0,1]
	v_pk_fma_f32 v[32:33], v[4:5], v[42:43], v[32:33] op_sel_hi:[1,0,1]
	v_pk_fma_f32 v[36:37], v[4:5], v[100:101], v[36:37] op_sel_hi:[1,0,1]
	v_pk_fma_f32 v[34:35], v[6:7], v[42:43], v[34:35] op_sel:[0,1,0]
	v_pk_fma_f32 v[38:39], v[6:7], v[100:101], v[38:39] op_sel:[0,1,0]
	v_pk_fma_f32 v[32:33], v[8:9], v[44:45], v[32:33] op_sel_hi:[1,0,1]
	v_pk_fma_f32 v[36:37], v[8:9], v[102:103], v[36:37] op_sel_hi:[1,0,1]
	v_pk_fma_f32 v[34:35], v[10:11], v[44:45], v[34:35] op_sel:[0,1,0]
	v_pk_fma_f32 v[38:39], v[10:11], v[102:103], v[38:39] op_sel:[0,1,0]
	v_pk_fma_f32 v[32:33], v[12:13], v[46:47], v[32:33] op_sel_hi:[1,0,1]
	v_pk_fma_f32 v[36:37], v[12:13], v[104:105], v[36:37] op_sel_hi:[1,0,1]
	v_pk_fma_f32 v[34:35], v[14:15], v[46:47], v[34:35] op_sel:[0,1,0]
	v_pk_fma_f32 v[38:39], v[14:15], v[104:105], v[38:39] op_sel:[0,1,0]
	v_pk_add_f32 v[36:37], v[36:37], v[38:39]
	v_pk_add_f32 v[32:33], v[32:33], v[34:35]
	ds_write2st64_b32 v134, v36, v37 offset0:2 offset1:3
	ds_read_b128 v[74:77], v132 offset:17328
	ds_read_b128 v[78:81], v132 offset:17344
	ds_read_b128 v[82:85], v132 offset:17584
	ds_read_b128 v[86:89], v132 offset:17600
	ds_read_b128 v[90:93], v132 offset:17840
	ds_read_b128 v[94:97], v132 offset:17856
	ds_read_b128 v[98:101], v132 offset:18096
	ds_read_b128 v[102:105], v132 offset:18112
	ds_read_b64 v[106:107], v133 offset:18352
	s_waitcnt lgkmcnt(10)
	v_add_f32_dpp v32, v32, v32 row_half_mirror row_mask:0xf bank_mask:0xf bound_ctrl:1
	v_add_f32_dpp v33, v33, v33 row_half_mirror row_mask:0xf bank_mask:0xf bound_ctrl:1
	v_pk_fma_f32 v[16:17], v[72:73], v[56:57], v[0:1] op_sel_hi:[1,0,1]
	v_add_f32_dpp v32, v32, v32 quad_perm:[1,0,3,2] row_mask:0xf bank_mask:0xf bound_ctrl:1
	v_add_f32_dpp v33, v33, v33 quad_perm:[1,0,3,2] row_mask:0xf bank_mask:0xf bound_ctrl:1
	v_pk_fma_f32 v[18:19], v[72:73], v[56:57], v[2:3] op_sel:[0,1,0]
	v_add_f32_dpp v32, v32, v32 quad_perm:[2,3,0,1] row_mask:0xf bank_mask:0xf bound_ctrl:1
	v_add_f32_dpp v33, v33, v33 quad_perm:[2,3,0,1] row_mask:0xf bank_mask:0xf bound_ctrl:1
	v_pk_fma_f32 v[20:21], v[72:73], v[58:59], v[4:5] op_sel_hi:[1,0,1]
	v_pk_fma_f32 v[22:23], v[72:73], v[58:59], v[6:7] op_sel:[0,1,0]
	v_pk_fma_f32 v[24:25], v[72:73], v[60:61], v[8:9] op_sel_hi:[1,0,1]
	v_pk_fma_f32 v[26:27], v[72:73], v[60:61], v[10:11] op_sel:[0,1,0]
	v_pk_fma_f32 v[28:29], v[72:73], v[62:63], v[12:13] op_sel_hi:[1,0,1]
	v_pk_fma_f32 v[30:31], v[72:73], v[62:63], v[14:15] op_sel:[0,1,0]
	v_pk_fma_f32 v[0:1], v[32:33], v[48:49], v[16:17] op_sel_hi:[1,0,1]
	v_pk_fma_f32 v[2:3], v[32:33], v[48:49], v[18:19] op_sel:[0,1,0]
	v_pk_fma_f32 v[4:5], v[32:33], v[50:51], v[20:21] op_sel_hi:[1,0,1]
	v_pk_fma_f32 v[6:7], v[32:33], v[50:51], v[22:23] op_sel:[0,1,0]
	v_pk_fma_f32 v[8:9], v[32:33], v[52:53], v[24:25] op_sel_hi:[1,0,1]
	v_pk_fma_f32 v[10:11], v[32:33], v[52:53], v[26:27] op_sel:[0,1,0]
	v_pk_fma_f32 v[12:13], v[32:33], v[54:55], v[28:29] op_sel_hi:[1,0,1]
	v_pk_fma_f32 v[14:15], v[32:33], v[54:55], v[30:31] op_sel:[0,1,0]
	s_waitcnt lgkmcnt(7)
	v_pk_mul_f32 v[32:33], v[0:1], v[74:75] op_sel_hi:[1,0]
	v_pk_mul_f32 v[36:37], v[0:1], v[64:65] op_sel_hi:[1,0]
	v_pk_mul_f32 v[34:35], v[2:3], v[74:75] op_sel:[0,1]
	v_pk_mul_f32 v[38:39], v[2:3], v[64:65] op_sel:[0,1]
	v_pk_fma_f32 v[32:33], v[4:5], v[76:77], v[32:33] op_sel_hi:[1,0,1]
	v_pk_fma_f32 v[36:37], v[4:5], v[66:67], v[36:37] op_sel_hi:[1,0,1]
	v_pk_fma_f32 v[34:35], v[6:7], v[76:77], v[34:35] op_sel:[0,1,0]
	v_pk_fma_f32 v[38:39], v[6:7], v[66:67], v[38:39] op_sel:[0,1,0]
	v_pk_fma_f32 v[32:33], v[8:9], v[78:79], v[32:33] op_sel_hi:[1,0,1]
	v_pk_fma_f32 v[36:37], v[8:9], v[68:69], v[36:37] op_sel_hi:[1,0,1]
	v_pk_fma_f32 v[34:35], v[10:11], v[78:79], v[34:35] op_sel:[0,1,0]
	v_pk_fma_f32 v[38:39], v[10:11], v[68:69], v[38:39] op_sel:[0,1,0]
	v_pk_fma_f32 v[32:33], v[12:13], v[80:81], v[32:33] op_sel_hi:[1,0,1]
	v_pk_fma_f32 v[36:37], v[12:13], v[70:71], v[36:37] op_sel_hi:[1,0,1]
	v_pk_fma_f32 v[34:35], v[14:15], v[80:81], v[34:35] op_sel:[0,1,0]
	v_pk_fma_f32 v[38:39], v[14:15], v[70:71], v[38:39] op_sel:[0,1,0]
	v_pk_add_f32 v[36:37], v[36:37], v[38:39]
	v_pk_add_f32 v[32:33], v[32:33], v[34:35]
	ds_write2st64_b32 v134, v36, v37 offset0:4 offset1:5
	ds_read_b128 v[40:43], v132 offset:18880
	ds_read_b128 v[44:47], v132 offset:18896
	ds_read_b128 v[48:51], v132 offset:19136
	ds_read_b128 v[52:55], v132 offset:19152
	ds_read_b128 v[56:59], v132 offset:19392
	ds_read_b128 v[60:63], v132 offset:19408
	ds_read_b128 v[64:67], v132 offset:19648
	ds_read_b128 v[68:71], v132 offset:19664
	ds_read_b64 v[72:73], v133 offset:19904
	s_waitcnt lgkmcnt(10)
	v_add_f32_dpp v32, v32, v32 row_half_mirror row_mask:0xf bank_mask:0xf bound_ctrl:1
	v_add_f32_dpp v33, v33, v33 row_half_mirror row_mask:0xf bank_mask:0xf bound_ctrl:1
	v_pk_fma_f32 v[16:17], v[106:107], v[90:91], v[0:1] op_sel_hi:[1,0,1]
	v_add_f32_dpp v32, v32, v32 quad_perm:[1,0,3,2] row_mask:0xf bank_mask:0xf bound_ctrl:1
	v_add_f32_dpp v33, v33, v33 quad_perm:[1,0,3,2] row_mask:0xf bank_mask:0xf bound_ctrl:1
	v_pk_fma_f32 v[18:19], v[106:107], v[90:91], v[2:3] op_sel:[0,1,0]
	v_add_f32_dpp v32, v32, v32 quad_perm:[2,3,0,1] row_mask:0xf bank_mask:0xf bound_ctrl:1
	v_add_f32_dpp v33, v33, v33 quad_perm:[2,3,0,1] row_mask:0xf bank_mask:0xf bound_ctrl:1
	v_pk_fma_f32 v[20:21], v[106:107], v[92:93], v[4:5] op_sel_hi:[1,0,1]
	v_pk_fma_f32 v[22:23], v[106:107], v[92:93], v[6:7] op_sel:[0,1,0]
	v_pk_fma_f32 v[24:25], v[106:107], v[94:95], v[8:9] op_sel_hi:[1,0,1]
	v_pk_fma_f32 v[26:27], v[106:107], v[94:95], v[10:11] op_sel:[0,1,0]
	v_pk_fma_f32 v[28:29], v[106:107], v[96:97], v[12:13] op_sel_hi:[1,0,1]
	v_pk_fma_f32 v[30:31], v[106:107], v[96:97], v[14:15] op_sel:[0,1,0]
	v_pk_fma_f32 v[0:1], v[32:33], v[82:83], v[16:17] op_sel_hi:[1,0,1]
	v_pk_fma_f32 v[2:3], v[32:33], v[82:83], v[18:19] op_sel:[0,1,0]
	v_pk_fma_f32 v[4:5], v[32:33], v[84:85], v[20:21] op_sel_hi:[1,0,1]
	v_pk_fma_f32 v[6:7], v[32:33], v[84:85], v[22:23] op_sel:[0,1,0]
	v_pk_fma_f32 v[8:9], v[32:33], v[86:87], v[24:25] op_sel_hi:[1,0,1]
	v_pk_fma_f32 v[10:11], v[32:33], v[86:87], v[26:27] op_sel:[0,1,0]
	v_pk_fma_f32 v[12:13], v[32:33], v[88:89], v[28:29] op_sel_hi:[1,0,1]
	v_pk_fma_f32 v[14:15], v[32:33], v[88:89], v[30:31] op_sel:[0,1,0]
	s_waitcnt lgkmcnt(7)
	v_pk_mul_f32 v[32:33], v[0:1], v[40:41] op_sel_hi:[1,0]
	v_pk_mul_f32 v[36:37], v[0:1], v[98:99] op_sel_hi:[1,0]
	v_pk_mul_f32 v[34:35], v[2:3], v[40:41] op_sel:[0,1]
	v_pk_mul_f32 v[38:39], v[2:3], v[98:99] op_sel:[0,1]
	v_pk_fma_f32 v[32:33], v[4:5], v[42:43], v[32:33] op_sel_hi:[1,0,1]
	v_pk_fma_f32 v[36:37], v[4:5], v[100:101], v[36:37] op_sel_hi:[1,0,1]
	v_pk_fma_f32 v[34:35], v[6:7], v[42:43], v[34:35] op_sel:[0,1,0]
	v_pk_fma_f32 v[38:39], v[6:7], v[100:101], v[38:39] op_sel:[0,1,0]
	v_pk_fma_f32 v[32:33], v[8:9], v[44:45], v[32:33] op_sel_hi:[1,0,1]
	v_pk_fma_f32 v[36:37], v[8:9], v[102:103], v[36:37] op_sel_hi:[1,0,1]
	v_pk_fma_f32 v[34:35], v[10:11], v[44:45], v[34:35] op_sel:[0,1,0]
	v_pk_fma_f32 v[38:39], v[10:11], v[102:103], v[38:39] op_sel:[0,1,0]
	v_pk_fma_f32 v[32:33], v[12:13], v[46:47], v[32:33] op_sel_hi:[1,0,1]
	v_pk_fma_f32 v[36:37], v[12:13], v[104:105], v[36:37] op_sel_hi:[1,0,1]
	v_pk_fma_f32 v[34:35], v[14:15], v[46:47], v[34:35] op_sel:[0,1,0]
	v_pk_fma_f32 v[38:39], v[14:15], v[104:105], v[38:39] op_sel:[0,1,0]
	v_pk_add_f32 v[36:37], v[36:37], v[38:39]
	v_pk_add_f32 v[32:33], v[32:33], v[34:35]
	ds_write2st64_b32 v134, v36, v37 offset0:6 offset1:7
	ds_read_b128 v[74:77], v132 offset:20432
	ds_read_b128 v[78:81], v132 offset:20448
	ds_read_b128 v[82:85], v132 offset:20688
	ds_read_b128 v[86:89], v132 offset:20704
	ds_read_b128 v[90:93], v132 offset:20944
	ds_read_b128 v[94:97], v132 offset:20960
	ds_read_b128 v[98:101], v132 offset:21200
	ds_read_b128 v[102:105], v132 offset:21216
	ds_read_b64 v[106:107], v133 offset:21456
	s_waitcnt lgkmcnt(10)
	v_add_f32_dpp v32, v32, v32 row_half_mirror row_mask:0xf bank_mask:0xf bound_ctrl:1
	v_add_f32_dpp v33, v33, v33 row_half_mirror row_mask:0xf bank_mask:0xf bound_ctrl:1
	v_pk_fma_f32 v[16:17], v[72:73], v[56:57], v[0:1] op_sel_hi:[1,0,1]
	v_add_f32_dpp v32, v32, v32 quad_perm:[1,0,3,2] row_mask:0xf bank_mask:0xf bound_ctrl:1
	v_add_f32_dpp v33, v33, v33 quad_perm:[1,0,3,2] row_mask:0xf bank_mask:0xf bound_ctrl:1
	v_pk_fma_f32 v[18:19], v[72:73], v[56:57], v[2:3] op_sel:[0,1,0]
	v_add_f32_dpp v32, v32, v32 quad_perm:[2,3,0,1] row_mask:0xf bank_mask:0xf bound_ctrl:1
	v_add_f32_dpp v33, v33, v33 quad_perm:[2,3,0,1] row_mask:0xf bank_mask:0xf bound_ctrl:1
	v_pk_fma_f32 v[20:21], v[72:73], v[58:59], v[4:5] op_sel_hi:[1,0,1]
	v_pk_fma_f32 v[22:23], v[72:73], v[58:59], v[6:7] op_sel:[0,1,0]
	v_pk_fma_f32 v[24:25], v[72:73], v[60:61], v[8:9] op_sel_hi:[1,0,1]
	v_pk_fma_f32 v[26:27], v[72:73], v[60:61], v[10:11] op_sel:[0,1,0]
	v_pk_fma_f32 v[28:29], v[72:73], v[62:63], v[12:13] op_sel_hi:[1,0,1]
	v_pk_fma_f32 v[30:31], v[72:73], v[62:63], v[14:15] op_sel:[0,1,0]
	v_pk_fma_f32 v[0:1], v[32:33], v[48:49], v[16:17] op_sel_hi:[1,0,1]
	v_pk_fma_f32 v[2:3], v[32:33], v[48:49], v[18:19] op_sel:[0,1,0]
	v_pk_fma_f32 v[4:5], v[32:33], v[50:51], v[20:21] op_sel_hi:[1,0,1]
	v_pk_fma_f32 v[6:7], v[32:33], v[50:51], v[22:23] op_sel:[0,1,0]
	v_pk_fma_f32 v[8:9], v[32:33], v[52:53], v[24:25] op_sel_hi:[1,0,1]
	v_pk_fma_f32 v[10:11], v[32:33], v[52:53], v[26:27] op_sel:[0,1,0]
	v_pk_fma_f32 v[12:13], v[32:33], v[54:55], v[28:29] op_sel_hi:[1,0,1]
	v_pk_fma_f32 v[14:15], v[32:33], v[54:55], v[30:31] op_sel:[0,1,0]
	s_waitcnt lgkmcnt(7)
	v_pk_mul_f32 v[32:33], v[0:1], v[74:75] op_sel_hi:[1,0]
	v_pk_mul_f32 v[36:37], v[0:1], v[64:65] op_sel_hi:[1,0]
	v_pk_mul_f32 v[34:35], v[2:3], v[74:75] op_sel:[0,1]
	v_pk_mul_f32 v[38:39], v[2:3], v[64:65] op_sel:[0,1]
	v_pk_fma_f32 v[32:33], v[4:5], v[76:77], v[32:33] op_sel_hi:[1,0,1]
	v_pk_fma_f32 v[36:37], v[4:5], v[66:67], v[36:37] op_sel_hi:[1,0,1]
	v_pk_fma_f32 v[34:35], v[6:7], v[76:77], v[34:35] op_sel:[0,1,0]
	v_pk_fma_f32 v[38:39], v[6:7], v[66:67], v[38:39] op_sel:[0,1,0]
	v_pk_fma_f32 v[32:33], v[8:9], v[78:79], v[32:33] op_sel_hi:[1,0,1]
	v_pk_fma_f32 v[36:37], v[8:9], v[68:69], v[36:37] op_sel_hi:[1,0,1]
	v_pk_fma_f32 v[34:35], v[10:11], v[78:79], v[34:35] op_sel:[0,1,0]
	v_pk_fma_f32 v[38:39], v[10:11], v[68:69], v[38:39] op_sel:[0,1,0]
	v_pk_fma_f32 v[32:33], v[12:13], v[80:81], v[32:33] op_sel_hi:[1,0,1]
	v_pk_fma_f32 v[36:37], v[12:13], v[70:71], v[36:37] op_sel_hi:[1,0,1]
	v_pk_fma_f32 v[34:35], v[14:15], v[80:81], v[34:35] op_sel:[0,1,0]
	v_pk_fma_f32 v[38:39], v[14:15], v[70:71], v[38:39] op_sel:[0,1,0]
	v_pk_add_f32 v[36:37], v[36:37], v[38:39]
	v_pk_add_f32 v[32:33], v[32:33], v[34:35]
	ds_write2st64_b32 v134, v36, v37 offset0:8 offset1:9
	ds_read_b128 v[40:43], v132 offset:21984
	ds_read_b128 v[44:47], v132 offset:22000
	ds_read_b128 v[48:51], v132 offset:22240
	ds_read_b128 v[52:55], v132 offset:22256
	ds_read_b128 v[56:59], v132 offset:22496
	ds_read_b128 v[60:63], v132 offset:22512
	ds_read_b128 v[64:67], v132 offset:22752
	ds_read_b128 v[68:71], v132 offset:22768
	ds_read_b64 v[72:73], v133 offset:23008
	s_waitcnt lgkmcnt(10)
	v_add_f32_dpp v32, v32, v32 row_half_mirror row_mask:0xf bank_mask:0xf bound_ctrl:1
	v_add_f32_dpp v33, v33, v33 row_half_mirror row_mask:0xf bank_mask:0xf bound_ctrl:1
	v_pk_fma_f32 v[16:17], v[106:107], v[90:91], v[0:1] op_sel_hi:[1,0,1]
	v_add_f32_dpp v32, v32, v32 quad_perm:[1,0,3,2] row_mask:0xf bank_mask:0xf bound_ctrl:1
	v_add_f32_dpp v33, v33, v33 quad_perm:[1,0,3,2] row_mask:0xf bank_mask:0xf bound_ctrl:1
	v_pk_fma_f32 v[18:19], v[106:107], v[90:91], v[2:3] op_sel:[0,1,0]
	v_add_f32_dpp v32, v32, v32 quad_perm:[2,3,0,1] row_mask:0xf bank_mask:0xf bound_ctrl:1
	v_add_f32_dpp v33, v33, v33 quad_perm:[2,3,0,1] row_mask:0xf bank_mask:0xf bound_ctrl:1
	v_pk_fma_f32 v[20:21], v[106:107], v[92:93], v[4:5] op_sel_hi:[1,0,1]
	v_pk_fma_f32 v[22:23], v[106:107], v[92:93], v[6:7] op_sel:[0,1,0]
	v_pk_fma_f32 v[24:25], v[106:107], v[94:95], v[8:9] op_sel_hi:[1,0,1]
	v_pk_fma_f32 v[26:27], v[106:107], v[94:95], v[10:11] op_sel:[0,1,0]
	v_pk_fma_f32 v[28:29], v[106:107], v[96:97], v[12:13] op_sel_hi:[1,0,1]
	v_pk_fma_f32 v[30:31], v[106:107], v[96:97], v[14:15] op_sel:[0,1,0]
	v_pk_fma_f32 v[0:1], v[32:33], v[82:83], v[16:17] op_sel_hi:[1,0,1]
	v_pk_fma_f32 v[2:3], v[32:33], v[82:83], v[18:19] op_sel:[0,1,0]
	v_pk_fma_f32 v[4:5], v[32:33], v[84:85], v[20:21] op_sel_hi:[1,0,1]
	v_pk_fma_f32 v[6:7], v[32:33], v[84:85], v[22:23] op_sel:[0,1,0]
	v_pk_fma_f32 v[8:9], v[32:33], v[86:87], v[24:25] op_sel_hi:[1,0,1]
	v_pk_fma_f32 v[10:11], v[32:33], v[86:87], v[26:27] op_sel:[0,1,0]
	v_pk_fma_f32 v[12:13], v[32:33], v[88:89], v[28:29] op_sel_hi:[1,0,1]
	v_pk_fma_f32 v[14:15], v[32:33], v[88:89], v[30:31] op_sel:[0,1,0]
	s_waitcnt lgkmcnt(7)
	v_pk_mul_f32 v[32:33], v[0:1], v[40:41] op_sel_hi:[1,0]
	v_pk_mul_f32 v[36:37], v[0:1], v[98:99] op_sel_hi:[1,0]
	v_pk_mul_f32 v[34:35], v[2:3], v[40:41] op_sel:[0,1]
	v_pk_mul_f32 v[38:39], v[2:3], v[98:99] op_sel:[0,1]
	v_pk_fma_f32 v[32:33], v[4:5], v[42:43], v[32:33] op_sel_hi:[1,0,1]
	v_pk_fma_f32 v[36:37], v[4:5], v[100:101], v[36:37] op_sel_hi:[1,0,1]
	v_pk_fma_f32 v[34:35], v[6:7], v[42:43], v[34:35] op_sel:[0,1,0]
	v_pk_fma_f32 v[38:39], v[6:7], v[100:101], v[38:39] op_sel:[0,1,0]
	v_pk_fma_f32 v[32:33], v[8:9], v[44:45], v[32:33] op_sel_hi:[1,0,1]
	v_pk_fma_f32 v[36:37], v[8:9], v[102:103], v[36:37] op_sel_hi:[1,0,1]
	v_pk_fma_f32 v[34:35], v[10:11], v[44:45], v[34:35] op_sel:[0,1,0]
	v_pk_fma_f32 v[38:39], v[10:11], v[102:103], v[38:39] op_sel:[0,1,0]
	v_pk_fma_f32 v[32:33], v[12:13], v[46:47], v[32:33] op_sel_hi:[1,0,1]
	v_pk_fma_f32 v[36:37], v[12:13], v[104:105], v[36:37] op_sel_hi:[1,0,1]
	v_pk_fma_f32 v[34:35], v[14:15], v[46:47], v[34:35] op_sel:[0,1,0]
	v_pk_fma_f32 v[38:39], v[14:15], v[104:105], v[38:39] op_sel:[0,1,0]
	v_pk_add_f32 v[36:37], v[36:37], v[38:39]
	v_pk_add_f32 v[32:33], v[32:33], v[34:35]
	ds_write2st64_b32 v134, v36, v37 offset0:10 offset1:11
	ds_read_b128 v[74:77], v132 offset:23536
	ds_read_b128 v[78:81], v132 offset:23552
	ds_read_b128 v[82:85], v132 offset:23792
	ds_read_b128 v[86:89], v132 offset:23808
	ds_read_b128 v[90:93], v132 offset:24048
	ds_read_b128 v[94:97], v132 offset:24064
	ds_read_b128 v[98:101], v132 offset:24304
	ds_read_b128 v[102:105], v132 offset:24320
	ds_read_b64 v[106:107], v133 offset:24560
	s_waitcnt lgkmcnt(10)
	v_add_f32_dpp v32, v32, v32 row_half_mirror row_mask:0xf bank_mask:0xf bound_ctrl:1
	v_add_f32_dpp v33, v33, v33 row_half_mirror row_mask:0xf bank_mask:0xf bound_ctrl:1
	v_pk_fma_f32 v[16:17], v[72:73], v[56:57], v[0:1] op_sel_hi:[1,0,1]
	v_add_f32_dpp v32, v32, v32 quad_perm:[1,0,3,2] row_mask:0xf bank_mask:0xf bound_ctrl:1
	v_add_f32_dpp v33, v33, v33 quad_perm:[1,0,3,2] row_mask:0xf bank_mask:0xf bound_ctrl:1
	v_pk_fma_f32 v[18:19], v[72:73], v[56:57], v[2:3] op_sel:[0,1,0]
	v_add_f32_dpp v32, v32, v32 quad_perm:[2,3,0,1] row_mask:0xf bank_mask:0xf bound_ctrl:1
	v_add_f32_dpp v33, v33, v33 quad_perm:[2,3,0,1] row_mask:0xf bank_mask:0xf bound_ctrl:1
	v_pk_fma_f32 v[20:21], v[72:73], v[58:59], v[4:5] op_sel_hi:[1,0,1]
	v_pk_fma_f32 v[22:23], v[72:73], v[58:59], v[6:7] op_sel:[0,1,0]
	v_pk_fma_f32 v[24:25], v[72:73], v[60:61], v[8:9] op_sel_hi:[1,0,1]
	v_pk_fma_f32 v[26:27], v[72:73], v[60:61], v[10:11] op_sel:[0,1,0]
	v_pk_fma_f32 v[28:29], v[72:73], v[62:63], v[12:13] op_sel_hi:[1,0,1]
	v_pk_fma_f32 v[30:31], v[72:73], v[62:63], v[14:15] op_sel:[0,1,0]
	v_pk_fma_f32 v[0:1], v[32:33], v[48:49], v[16:17] op_sel_hi:[1,0,1]
	v_pk_fma_f32 v[2:3], v[32:33], v[48:49], v[18:19] op_sel:[0,1,0]
	v_pk_fma_f32 v[4:5], v[32:33], v[50:51], v[20:21] op_sel_hi:[1,0,1]
	v_pk_fma_f32 v[6:7], v[32:33], v[50:51], v[22:23] op_sel:[0,1,0]
	v_pk_fma_f32 v[8:9], v[32:33], v[52:53], v[24:25] op_sel_hi:[1,0,1]
	v_pk_fma_f32 v[10:11], v[32:33], v[52:53], v[26:27] op_sel:[0,1,0]
	v_pk_fma_f32 v[12:13], v[32:33], v[54:55], v[28:29] op_sel_hi:[1,0,1]
	v_pk_fma_f32 v[14:15], v[32:33], v[54:55], v[30:31] op_sel:[0,1,0]
	s_waitcnt lgkmcnt(7)
	v_pk_mul_f32 v[32:33], v[0:1], v[74:75] op_sel_hi:[1,0]
	v_pk_mul_f32 v[36:37], v[0:1], v[64:65] op_sel_hi:[1,0]
	v_pk_mul_f32 v[34:35], v[2:3], v[74:75] op_sel:[0,1]
	v_pk_mul_f32 v[38:39], v[2:3], v[64:65] op_sel:[0,1]
	v_pk_fma_f32 v[32:33], v[4:5], v[76:77], v[32:33] op_sel_hi:[1,0,1]
	v_pk_fma_f32 v[36:37], v[4:5], v[66:67], v[36:37] op_sel_hi:[1,0,1]
	v_pk_fma_f32 v[34:35], v[6:7], v[76:77], v[34:35] op_sel:[0,1,0]
	v_pk_fma_f32 v[38:39], v[6:7], v[66:67], v[38:39] op_sel:[0,1,0]
	v_pk_fma_f32 v[32:33], v[8:9], v[78:79], v[32:33] op_sel_hi:[1,0,1]
	v_pk_fma_f32 v[36:37], v[8:9], v[68:69], v[36:37] op_sel_hi:[1,0,1]
	v_pk_fma_f32 v[34:35], v[10:11], v[78:79], v[34:35] op_sel:[0,1,0]
	v_pk_fma_f32 v[38:39], v[10:11], v[68:69], v[38:39] op_sel:[0,1,0]
	v_pk_fma_f32 v[32:33], v[12:13], v[80:81], v[32:33] op_sel_hi:[1,0,1]
	v_pk_fma_f32 v[36:37], v[12:13], v[70:71], v[36:37] op_sel_hi:[1,0,1]
	v_pk_fma_f32 v[34:35], v[14:15], v[80:81], v[34:35] op_sel:[0,1,0]
	v_pk_fma_f32 v[38:39], v[14:15], v[70:71], v[38:39] op_sel:[0,1,0]
	v_pk_add_f32 v[36:37], v[36:37], v[38:39]
	v_pk_add_f32 v[32:33], v[32:33], v[34:35]
	ds_write2st64_b32 v134, v36, v37 offset0:12 offset1:13
	ds_read_b128 v[108:111], v132 offset:23280
	ds_read_b128 v[112:115], v132 offset:23296
	s_waitcnt lgkmcnt(3)
	v_add_f32_dpp v32, v32, v32 row_half_mirror row_mask:0xf bank_mask:0xf bound_ctrl:1
	v_add_f32_dpp v33, v33, v33 row_half_mirror row_mask:0xf bank_mask:0xf bound_ctrl:1
	v_pk_fma_f32 v[16:17], v[106:107], v[90:91], v[0:1] op_sel_hi:[1,0,1]
	v_add_f32_dpp v32, v32, v32 quad_perm:[1,0,3,2] row_mask:0xf bank_mask:0xf bound_ctrl:1
	v_add_f32_dpp v33, v33, v33 quad_perm:[1,0,3,2] row_mask:0xf bank_mask:0xf bound_ctrl:1
	v_pk_fma_f32 v[18:19], v[106:107], v[90:91], v[2:3] op_sel:[0,1,0]
	v_add_f32_dpp v32, v32, v32 quad_perm:[2,3,0,1] row_mask:0xf bank_mask:0xf bound_ctrl:1
	v_add_f32_dpp v33, v33, v33 quad_perm:[2,3,0,1] row_mask:0xf bank_mask:0xf bound_ctrl:1
	v_pk_fma_f32 v[20:21], v[106:107], v[92:93], v[4:5] op_sel_hi:[1,0,1]
	v_pk_fma_f32 v[22:23], v[106:107], v[92:93], v[6:7] op_sel:[0,1,0]
	v_pk_fma_f32 v[24:25], v[106:107], v[94:95], v[8:9] op_sel_hi:[1,0,1]
	v_pk_fma_f32 v[26:27], v[106:107], v[94:95], v[10:11] op_sel:[0,1,0]
	v_pk_fma_f32 v[28:29], v[106:107], v[96:97], v[12:13] op_sel_hi:[1,0,1]
	v_pk_fma_f32 v[30:31], v[106:107], v[96:97], v[14:15] op_sel:[0,1,0]
	v_pk_fma_f32 v[0:1], v[32:33], v[82:83], v[16:17] op_sel_hi:[1,0,1]
	v_pk_fma_f32 v[2:3], v[32:33], v[82:83], v[18:19] op_sel:[0,1,0]
	v_pk_fma_f32 v[4:5], v[32:33], v[84:85], v[20:21] op_sel_hi:[1,0,1]
	v_pk_fma_f32 v[6:7], v[32:33], v[84:85], v[22:23] op_sel:[0,1,0]
	v_pk_fma_f32 v[8:9], v[32:33], v[86:87], v[24:25] op_sel_hi:[1,0,1]
	v_pk_fma_f32 v[10:11], v[32:33], v[86:87], v[26:27] op_sel:[0,1,0]
	v_pk_fma_f32 v[12:13], v[32:33], v[88:89], v[28:29] op_sel_hi:[1,0,1]
	v_pk_fma_f32 v[14:15], v[32:33], v[88:89], v[30:31] op_sel:[0,1,0]
	v_pk_mul_f32 v[36:37], v[0:1], v[98:99] op_sel_hi:[1,0]
	v_pk_mul_f32 v[38:39], v[2:3], v[98:99] op_sel:[0,1]
	v_pk_fma_f32 v[36:37], v[4:5], v[100:101], v[36:37] op_sel_hi:[1,0,1]
	v_pk_fma_f32 v[38:39], v[6:7], v[100:101], v[38:39] op_sel:[0,1,0]
	v_pk_fma_f32 v[36:37], v[8:9], v[102:103], v[36:37] op_sel_hi:[1,0,1]
	v_pk_fma_f32 v[38:39], v[10:11], v[102:103], v[38:39] op_sel:[0,1,0]
	v_pk_fma_f32 v[36:37], v[12:13], v[104:105], v[36:37] op_sel_hi:[1,0,1]
	v_pk_fma_f32 v[38:39], v[14:15], v[104:105], v[38:39] op_sel:[0,1,0]
	v_pk_add_f32 v[36:37], v[36:37], v[38:39]
	ds_write2st64_b32 v134, v36, v37 offset0:14 offset1:15
	ds_read_b128 v[116:119], v135
	ds_read_b128 v[120:123], v135 offset:16
	ds_read_b128 v[124:127], v135 offset:2048
	ds_read_b128 v[128:131], v135 offset:2064
	s_waitcnt lgkmcnt(2)
	v_pk_add_f32 v[116:117], v[116:117], v[118:119]
	v_pk_add_f32 v[120:121], v[120:121], v[122:123]
	s_waitcnt lgkmcnt(0)
	v_pk_add_f32 v[124:125], v[124:125], v[126:127]
	v_pk_add_f32 v[128:129], v[128:129], v[130:131]
	v_pk_add_f32 v[116:117], v[116:117], v[120:121]
	v_pk_add_f32 v[124:125], v[124:125], v[128:129]
	v_add_f32_e32 v116, v116, v117
	v_add_f32_e32 v124, v124, v125
	global_atomic_add_f32 v[136:137], v116, off
	global_atomic_add_f32 v[138:139], v124, off
	v_lshl_add_u64 v[136:137], v[136:137], 0, s[38:39]
	v_lshl_add_u64 v[138:139], v[138:139], 0, s[38:39]
	v_pk_mul_f32 v[0:1], v[0:1], v[108:109] op_sel_hi:[1,0]
	v_pk_mul_f32 v[2:3], v[2:3], v[108:109] op_sel:[0,1]
	v_pk_mul_f32 v[4:5], v[4:5], v[110:111] op_sel_hi:[1,0]
	v_pk_mul_f32 v[6:7], v[6:7], v[110:111] op_sel:[0,1]
	v_pk_mul_f32 v[8:9], v[8:9], v[112:113] op_sel_hi:[1,0]
	v_pk_mul_f32 v[10:11], v[10:11], v[112:113] op_sel:[0,1]
	v_pk_mul_f32 v[12:13], v[12:13], v[114:115] op_sel_hi:[1,0]
	v_pk_mul_f32 v[14:15], v[14:15], v[114:115] op_sel:[0,1]
	s_xor_b32 s75, s75, 0x6100
	s_waitcnt lgkmcnt(0)
	s_barrier
	s_add_i32 s74, s74, 1
	s_cmp_lt_u32 s74, s73
	s_cbranch_scc1 .Lst_chunk
	s_cmp_eq_u32 s70, 0
	s_cbranch_scc1 .Lst_item_next
	v_mov_b32_e32 v164, v0
	v_mov_b32_e32 v172, v1
	v_mov_b32_e32 v165, v2
	v_mov_b32_e32 v173, v3
	v_mov_b32_e32 v166, v4
	v_mov_b32_e32 v174, v5
	v_mov_b32_e32 v167, v6
	v_mov_b32_e32 v175, v7
	v_mov_b32_e32 v168, v8
	v_mov_b32_e32 v176, v9
	v_mov_b32_e32 v169, v10
	v_mov_b32_e32 v177, v11
	v_mov_b32_e32 v170, v12
	v_mov_b32_e32 v178, v13
	v_mov_b32_e32 v171, v14
	v_mov_b32_e32 v179, v15
	s_add_u32 s4, s20, 0x9000000
	s_addc_u32 s5, s21, 0
	s_add_u32 s4, s4, s40
	s_addc_u32 s5, s5, s41
	v_lshl_add_u64 v[182:183], v[184:185], 0, s[4:5]
	global_store_dwordx4 v[182:183], v[164:167], off
	global_store_dwordx4 v[182:183], v[168:171], off offset:16
	global_store_dwordx4 v[182:183], v[172:175], off offset:256
	global_store_dwordx4 v[182:183], v[176:179], off offset:272

.Lst_seg_next:
	s_add_i32 s70, s70, 1
	s_cmp_lt_u32 s70, 2
	s_cbranch_scc1 .Lst_seg
	s_mov_b64 s[74:75], 0xc80000
	s_setprio 0
	s_branch .LBB0_341
